# K-loop control scalars issued 8 MFMAs before the end of the last block (deeper in the MFMA shadow)
# baseline (speedup 1.0000x reference)
; #define PG8_STAGE(bufoff, gbase, voff) do { _Pragma("unroll") for (int _i = 0; _i < 2; ++_i) \
;         __builtin_amdgcn_global_load_lds((const unsigned*)((const char*)(gbase) + (voff)[_i]), (PG8_LAS unsigned*)(lds + (bufoff) + ldsw + _i * 8192), 16, 0, 0); } while (0)
; #define PG8_LDA(dst, b, h) do { _Pragma("unroll") for (int m = 0; m < 4; ++m) _Pragma("unroll") for (int k = 0; k < 2; ++k) dst[m][k] = *(const PG8_LAS bf16x8*)(lds + PG8_SA(b, h) + aoff + m * 2048 + k * 1024); } while (0)
; #define PG8_LDB(dst, b, h) do { _Pragma("unroll") for (int n = 0; n < 2; ++n) _Pragma("unroll") for (int k = 0; k < 2; ++k) dst[n][k] = *(const PG8_LAS bf16x8*)(lds + PG8_SB(b, h) + boff + n * 2048 + k * 1024); } while (0)
; #define PG8_MMA(ai, bj, At, Bt) do { __builtin_amdgcn_s_setprio(1); _Pragma("unroll") for (int m = 0; m < 4; ++m) _Pragma("unroll") for (int n = 0; n < 2; ++n) _Pragma("unroll") for (int k = 0; k < 2; ++k) \
;         acc[ai][bj][m][n] = __builtin_amdgcn_mfma_f32_16x16x32_bf16(Bt[n][k], At[m][k], acc[ai][bj][m][n], 0, 0, 0); __builtin_amdgcn_s_setprio(0); } while (0)
; #define PG8_WAIT_V(n) asm volatile("s_waitcnt vmcnt(" #n ")" ::: "memory")
; #define PG8_WAIT_L(n) asm volatile("s_waitcnt lgkmcnt(" #n ")" ::: "memory")
; template <class Epi, class Sched, bool ALIGN_EPI = false, bool SP2 = false>
; __device__ __forceinline__ void gemm_phase(PG8_LAS unsigned char* lds, const Gemm g, const Sched S, const Epi E) {
;     ...
;             const bool last = (t == nt - 2);
;             const char* a1 = cA + (size_t)(t + 1) * kstep;
;             const char* a2 = last ? nA : cA + (size_t)(t + 2) * kstep; const char* b2 = last ? nB : cB + (size_t)(t + 2) * kstep;
;             const char* a3 = a2 + kstep; const char* b3 = b2 + kstep;
;             if (last && has_next) S.a_ready(nxt);
;             if constexpr (SP2) {
;             PG8_LDB(B0, 0, 0); PG8_LDB(B1, 0, 1); PG8_SCHED; PG8_LDA(At, 0, 0); PG8_STAGE(PG8_SA(1, 1), a1 + hstep, voffA);
;             PG8_WAIT_V(8); PG8_WAIT_L(0); PG8_BAR; PG8_MMA(0, 0, At, B0); PG8_MMA(0, 1, At, B1); PG8_BAR; PG8_SCHED;
;             PG8_LDA(At, 0, 1); PG8_STAGE(PG8_SB(0, 0), b2, voffB); PG8_STAGE(PG8_SB(0, 1), b2 + hstep, voffB); PG8_STAGE(PG8_SA(0, 0), a2, voffA);
;             PG8_WAIT_V(8); PG8_WAIT_L(0); PG8_BAR; PG8_MMA(1, 0, At, B0); PG8_MMA(1, 1, At, B1); PG8_BAR; PG8_SCHED;
.Lpagefit_1:
.LBB0_276:
	ds_read_b128 v[152:155], v149
	ds_read_b128 v[156:159], v149 offset:1024
	ds_read_b128 v[160:163], v149 offset:2048
	ds_read_b128 v[164:167], v149 offset:3072
	ds_read_b128 v[168:171], v150
	ds_read_b128 v[172:175], v150 offset:1024
	ds_read_b128 v[176:179], v150 offset:2048
	ds_read_b128 v[180:183], v150 offset:3072
	s_add_u32 s44, s42, 0xfffc0080
	s_addc_u32 s45, s43, -1
	s_cmp_eq_u32 s69, 12
	s_cselect_b32 s51, s19, s45
	s_cselect_b32 s50, s63, s44
	s_cselect_b32 s45, s17, s68
	s_cselect_b32 s44, s64, s65
	v_lshl_add_u64 v[144:145], s[42:43], 0, v[136:137]
	s_add_i32 m0, s33, 0xc000
	ds_read_b128 v[190:193], v151
	ds_read_b128 v[194:197], v151 offset:1024
	ds_read_b128 v[198:201], v151 offset:2048
	ds_read_b128 v[202:205], v151 offset:3072
	ds_read_b128 v[206:209], v151 offset:4096
	ds_read_b128 v[210:213], v151 offset:5120
	ds_read_b128 v[214:217], v151 offset:6144
	ds_read_b128 v[218:221], v151 offset:7168
	global_load_lds_dwordx4 v[144:145], off
	v_lshl_add_u64 v[144:145], s[42:43], 0, v[138:139]
	s_add_i32 m0, s33, 0xe000
	s_nop 0
	global_load_lds_dwordx4 v[144:145], off
	s_waitcnt vmcnt(8)
	s_waitcnt lgkmcnt(0)
	s_barrier
	s_setprio 1
	s_waitcnt lgkmcnt(0)
	v_mfma_f32_16x16x32_bf16 v[124:127], v[152:155], v[190:193], v[124:127]
	v_mfma_f32_16x16x32_bf16 v[116:119], v[160:163], v[190:193], v[116:119]
	v_mfma_f32_16x16x32_bf16 v[108:111], v[152:155], v[198:201], v[108:111]
	v_mfma_f32_16x16x32_bf16 v[100:103], v[160:163], v[198:201], v[100:103]
	v_mfma_f32_16x16x32_bf16 v[92:95], v[152:155], v[206:209], v[92:95]
	v_mfma_f32_16x16x32_bf16 v[84:87], v[160:163], v[206:209], v[84:87]
	v_mfma_f32_16x16x32_bf16 v[76:79], v[152:155], v[214:217], v[76:79]
	v_mfma_f32_16x16x32_bf16 v[68:71], v[160:163], v[214:217], v[68:71]
	v_mfma_f32_16x16x32_bf16 v[124:127], v[156:159], v[194:197], v[124:127]
	v_mfma_f32_16x16x32_bf16 v[116:119], v[164:167], v[194:197], v[116:119]
	v_mfma_f32_16x16x32_bf16 v[108:111], v[156:159], v[202:205], v[108:111]
	v_mfma_f32_16x16x32_bf16 v[100:103], v[164:167], v[202:205], v[100:103]
	v_mfma_f32_16x16x32_bf16 v[92:95], v[156:159], v[210:213], v[92:95]
	v_mfma_f32_16x16x32_bf16 v[84:87], v[164:167], v[210:213], v[84:87]
	v_mfma_f32_16x16x32_bf16 v[76:79], v[156:159], v[218:221], v[76:79]
	v_mfma_f32_16x16x32_bf16 v[68:71], v[164:167], v[218:221], v[68:71]
	s_setprio 0
	s_setprio 1
	v_mfma_f32_16x16x32_bf16 v[120:123], v[168:171], v[190:193], v[120:123]
	v_mfma_f32_16x16x32_bf16 v[112:115], v[176:179], v[190:193], v[112:115]
	v_mfma_f32_16x16x32_bf16 v[104:107], v[168:171], v[198:201], v[104:107]
	v_mfma_f32_16x16x32_bf16 v[96:99], v[176:179], v[198:201], v[96:99]
	v_mfma_f32_16x16x32_bf16 v[88:91], v[168:171], v[206:209], v[88:91]
	v_mfma_f32_16x16x32_bf16 v[80:83], v[176:179], v[206:209], v[80:83]
	v_mfma_f32_16x16x32_bf16 v[72:75], v[168:171], v[214:217], v[72:75]
	v_mfma_f32_16x16x32_bf16 v[64:67], v[176:179], v[214:217], v[64:67]
	v_mfma_f32_16x16x32_bf16 v[120:123], v[172:175], v[194:197], v[120:123]
	v_mfma_f32_16x16x32_bf16 v[112:115], v[180:183], v[194:197], v[112:115]
	v_mfma_f32_16x16x32_bf16 v[104:107], v[172:175], v[202:205], v[104:107]
	v_mfma_f32_16x16x32_bf16 v[96:99], v[180:183], v[202:205], v[96:99]
	v_mfma_f32_16x16x32_bf16 v[88:91], v[172:175], v[210:213], v[88:91]
	v_mfma_f32_16x16x32_bf16 v[80:83], v[180:183], v[210:213], v[80:83]
	v_mfma_f32_16x16x32_bf16 v[72:75], v[172:175], v[218:221], v[72:75]
	v_mfma_f32_16x16x32_bf16 v[64:67], v[180:183], v[218:221], v[64:67]
	s_setprio 0
	s_barrier
	s_add_i32 s82, s59, s8
	v_lshl_add_u64 v[144:145], s[44:45], 0, v[132:133]
	s_mov_b32 m0, s82
	ds_read_b128 v[190:193], v151 offset:16384
	ds_read_b128 v[194:197], v151 offset:17408
	ds_read_b128 v[198:201], v151 offset:18432
	ds_read_b128 v[202:205], v151 offset:19456
	ds_read_b128 v[206:209], v151 offset:20480
	ds_read_b128 v[210:213], v151 offset:21504
	ds_read_b128 v[214:217], v151 offset:22528
	ds_read_b128 v[218:221], v151 offset:23552
	global_load_lds_dwordx4 v[144:145], off
	s_add_i32 m0, s82, 0x2000
	s_add_u32 s82, s44, 0x40000
	v_lshl_add_u64 v[184:185], s[44:45], 0, v[128:129]
	s_addc_u32 s83, s45, 0
	s_add_i32 s84, s60, s8
	global_load_lds_dwordx4 v[184:185], off
	v_lshl_add_u64 v[222:223], s[82:83], 0, v[132:133]
	s_mov_b32 m0, s84
	v_lshl_add_u64 v[224:225], s[50:51], 0, v[130:131]
	global_load_lds_dwordx4 v[222:223], off
	v_lshl_add_u64 v[222:223], s[82:83], 0, v[128:129]
	s_add_i32 m0, s84, 0x2000
	s_nop 0
	global_load_lds_dwordx4 v[222:223], off
	v_lshl_add_u64 v[222:223], s[50:51], 0, v[134:135]
	s_mov_b32 m0, s33
	s_nop 0
	global_load_lds_dwordx4 v[222:223], off
	s_mov_b32 m0, s36
	s_nop 0
	global_load_lds_dwordx4 v[224:225], off
	s_waitcnt vmcnt(8)
	s_waitcnt lgkmcnt(0)
	s_barrier
; #define PG8_STAGE(bufoff, gbase, voff) do { _Pragma("unroll") for (int _i = 0; _i < 2; ++_i) \
;         __builtin_amdgcn_global_load_lds((const unsigned*)((const char*)(gbase) + (voff)[_i]), (PG8_LAS unsigned*)(lds + (bufoff) + ldsw + _i * 8192), 16, 0, 0); } while (0)
; #define PG8_LDA(dst, b, h) do { _Pragma("unroll") for (int m = 0; m < 4; ++m) _Pragma("unroll") for (int k = 0; k < 2; ++k) dst[m][k] = *(const PG8_LAS bf16x8*)(lds + PG8_SA(b, h) + aoff + m * 2048 + k * 1024); } while (0)
; #define PG8_LDB(dst, b, h) do { _Pragma("unroll") for (int n = 0; n < 2; ++n) _Pragma("unroll") for (int k = 0; k < 2; ++k) dst[n][k] = *(const PG8_LAS bf16x8*)(lds + PG8_SB(b, h) + boff + n * 2048 + k * 1024); } while (0)
; #define PG8_MMA(ai, bj, At, Bt) do { __builtin_amdgcn_s_setprio(1); _Pragma("unroll") for (int m = 0; m < 4; ++m) _Pragma("unroll") for (int n = 0; n < 2; ++n) _Pragma("unroll") for (int k = 0; k < 2; ++k) \
;         acc[ai][bj][m][n] = __builtin_amdgcn_mfma_f32_16x16x32_bf16(Bt[n][k], At[m][k], acc[ai][bj][m][n], 0, 0, 0); __builtin_amdgcn_s_setprio(0); } while (0)
; #define PG8_WAIT_V(n) asm volatile("s_waitcnt vmcnt(" #n ")" ::: "memory")
; #define PG8_WAIT_L(n) asm volatile("s_waitcnt lgkmcnt(" #n ")" ::: "memory")
; #define PG8_BAR __builtin_amdgcn_s_barrier()
; #define PG8_SCHED __builtin_amdgcn_sched_barrier(0)
; template <class Epi, class Sched, bool ALIGN_EPI = false, bool SP2 = false>
; __device__ __forceinline__ void gemm_phase(PG8_LAS unsigned char* lds, const Gemm g, const Sched S, const Epi E) {
;     ...
;             PG8_WAIT_V(8); PG8_WAIT_L(0); PG8_BAR; PG8_MMA(1, 0, At, B0); PG8_MMA(1, 1, At, B1); PG8_BAR; PG8_SCHED;
;             PG8_LDB(B0, 1, 0); PG8_LDB(B1, 1, 1); PG8_SCHED; PG8_LDA(At, 1, 0); PG8_STAGE(PG8_SA(0, 1), a2 + hstep, voffA);
;             PG8_WAIT_V(8); PG8_WAIT_L(0); PG8_BAR; PG8_MMA(0, 0, At, B0); PG8_MMA(0, 1, At, B1); PG8_BAR; PG8_SCHED;
	s_setprio 1
	s_waitcnt lgkmcnt(0)
	v_mfma_f32_16x16x32_bf16 v[60:63], v[152:155], v[190:193], v[60:63]
	v_mfma_f32_16x16x32_bf16 v[52:55], v[160:163], v[190:193], v[52:55]
	v_mfma_f32_16x16x32_bf16 v[44:47], v[152:155], v[198:201], v[44:47]
	v_mfma_f32_16x16x32_bf16 v[36:39], v[160:163], v[198:201], v[36:39]
	v_mfma_f32_16x16x32_bf16 v[28:31], v[152:155], v[206:209], v[28:31]
	v_mfma_f32_16x16x32_bf16 v[20:23], v[160:163], v[206:209], v[20:23]
	v_mfma_f32_16x16x32_bf16 v[12:15], v[152:155], v[214:217], v[12:15]
	v_mfma_f32_16x16x32_bf16 v[4:7], v[160:163], v[214:217], v[4:7]
	v_mfma_f32_16x16x32_bf16 v[60:63], v[156:159], v[194:197], v[60:63]
	v_mfma_f32_16x16x32_bf16 v[52:55], v[164:167], v[194:197], v[52:55]
	v_mfma_f32_16x16x32_bf16 v[44:47], v[156:159], v[202:205], v[44:47]
	v_mfma_f32_16x16x32_bf16 v[36:39], v[164:167], v[202:205], v[36:39]
	v_mfma_f32_16x16x32_bf16 v[28:31], v[156:159], v[210:213], v[28:31]
	v_mfma_f32_16x16x32_bf16 v[20:23], v[164:167], v[210:213], v[20:23]
	v_mfma_f32_16x16x32_bf16 v[12:15], v[156:159], v[218:221], v[12:15]
	v_mfma_f32_16x16x32_bf16 v[4:7], v[164:167], v[218:221], v[4:7]
	s_setprio 0
	s_setprio 1
	v_mfma_f32_16x16x32_bf16 v[56:59], v[168:171], v[190:193], v[56:59]
	v_mfma_f32_16x16x32_bf16 v[48:51], v[176:179], v[190:193], v[48:51]
	v_mfma_f32_16x16x32_bf16 v[40:43], v[168:171], v[198:201], v[40:43]
	v_mfma_f32_16x16x32_bf16 v[32:35], v[176:179], v[198:201], v[32:35]
	v_mfma_f32_16x16x32_bf16 v[24:27], v[168:171], v[206:209], v[24:27]
	v_mfma_f32_16x16x32_bf16 v[16:19], v[176:179], v[206:209], v[16:19]
	v_mfma_f32_16x16x32_bf16 v[8:11], v[168:171], v[214:217], v[8:11]
	v_mfma_f32_16x16x32_bf16 v[0:3], v[176:179], v[214:217], v[0:3]
	v_mfma_f32_16x16x32_bf16 v[56:59], v[172:175], v[194:197], v[56:59]
	v_mfma_f32_16x16x32_bf16 v[48:51], v[180:183], v[194:197], v[48:51]
	v_mfma_f32_16x16x32_bf16 v[40:43], v[172:175], v[202:205], v[40:43]
	v_mfma_f32_16x16x32_bf16 v[32:35], v[180:183], v[202:205], v[32:35]
	v_mfma_f32_16x16x32_bf16 v[24:27], v[172:175], v[210:213], v[24:27]
	v_mfma_f32_16x16x32_bf16 v[16:19], v[180:183], v[210:213], v[16:19]
	v_mfma_f32_16x16x32_bf16 v[8:11], v[172:175], v[218:221], v[8:11]
	v_mfma_f32_16x16x32_bf16 v[0:3], v[180:183], v[218:221], v[0:3]
	s_setprio 0
	s_barrier
	s_add_i32 s82, 0, 0x18000
	s_add_i32 s83, 0, 0x1c000
	v_add_u32_e32 v164, s82, v148
	v_add_u32_e32 v180, s83, v148
	ds_read_b128 v[152:155], v164
	ds_read_b128 v[156:159], v164 offset:1024
	ds_read_b128 v[160:163], v164 offset:2048
	ds_read_b128 v[164:167], v164 offset:3072
	ds_read_b128 v[168:171], v180
	ds_read_b128 v[172:175], v180 offset:1024
	ds_read_b128 v[176:179], v180 offset:2048
	ds_read_b128 v[180:183], v180 offset:3072
	s_add_u32 s50, s50, 0x40000
	s_addc_u32 s51, s51, 0
	s_mov_b32 m0, s37
	v_lshl_add_u64 v[226:227], s[50:51], 0, v[134:135]
	ds_read_b128 v[190:193], v151 offset:32768
	ds_read_b128 v[194:197], v151 offset:33792
	ds_read_b128 v[198:201], v151 offset:34816
	ds_read_b128 v[202:205], v151 offset:35840
	ds_read_b128 v[206:209], v151 offset:36864
	ds_read_b128 v[210:213], v151 offset:37888
	ds_read_b128 v[214:217], v151 offset:38912
	ds_read_b128 v[218:221], v151 offset:39936
	global_load_lds_dwordx4 v[226:227], off
	v_lshl_add_u64 v[226:227], s[50:51], 0, v[130:131]
	s_mov_b32 m0, s41
	s_nop 0
	global_load_lds_dwordx4 v[226:227], off
	s_waitcnt vmcnt(8)
	s_waitcnt lgkmcnt(0)
	s_barrier
	s_setprio 1
	s_waitcnt lgkmcnt(0)
	v_mfma_f32_16x16x32_bf16 v[124:127], v[152:155], v[190:193], v[124:127]
	v_mfma_f32_16x16x32_bf16 v[116:119], v[160:163], v[190:193], v[116:119]
	v_mfma_f32_16x16x32_bf16 v[108:111], v[152:155], v[198:201], v[108:111]
	v_mfma_f32_16x16x32_bf16 v[100:103], v[160:163], v[198:201], v[100:103]
	v_mfma_f32_16x16x32_bf16 v[92:95], v[152:155], v[206:209], v[92:95]
	v_mfma_f32_16x16x32_bf16 v[84:87], v[160:163], v[206:209], v[84:87]
	v_mfma_f32_16x16x32_bf16 v[76:79], v[152:155], v[214:217], v[76:79]
	v_mfma_f32_16x16x32_bf16 v[68:71], v[160:163], v[214:217], v[68:71]
	v_mfma_f32_16x16x32_bf16 v[124:127], v[156:159], v[194:197], v[124:127]
	v_mfma_f32_16x16x32_bf16 v[116:119], v[164:167], v[194:197], v[116:119]
	v_mfma_f32_16x16x32_bf16 v[108:111], v[156:159], v[202:205], v[108:111]
	v_mfma_f32_16x16x32_bf16 v[100:103], v[164:167], v[202:205], v[100:103]
	v_mfma_f32_16x16x32_bf16 v[92:95], v[156:159], v[210:213], v[92:95]
	v_mfma_f32_16x16x32_bf16 v[84:87], v[164:167], v[210:213], v[84:87]
	v_mfma_f32_16x16x32_bf16 v[76:79], v[156:159], v[218:221], v[76:79]
	v_mfma_f32_16x16x32_bf16 v[68:71], v[164:167], v[218:221], v[68:71]
	s_setprio 0
	s_setprio 1
	v_mfma_f32_16x16x32_bf16 v[120:123], v[168:171], v[190:193], v[120:123]
	v_mfma_f32_16x16x32_bf16 v[112:115], v[176:179], v[190:193], v[112:115]
	v_mfma_f32_16x16x32_bf16 v[104:107], v[168:171], v[198:201], v[104:107]
	v_mfma_f32_16x16x32_bf16 v[96:99], v[176:179], v[198:201], v[96:99]
	v_mfma_f32_16x16x32_bf16 v[88:91], v[168:171], v[206:209], v[88:91]
	v_mfma_f32_16x16x32_bf16 v[80:83], v[176:179], v[206:209], v[80:83]
	v_mfma_f32_16x16x32_bf16 v[72:75], v[168:171], v[214:217], v[72:75]
	v_mfma_f32_16x16x32_bf16 v[64:67], v[176:179], v[214:217], v[64:67]
	v_mfma_f32_16x16x32_bf16 v[120:123], v[172:175], v[194:197], v[120:123]
	v_mfma_f32_16x16x32_bf16 v[112:115], v[180:183], v[194:197], v[112:115]
	v_mfma_f32_16x16x32_bf16 v[104:107], v[172:175], v[202:205], v[104:107]
	v_mfma_f32_16x16x32_bf16 v[96:99], v[180:183], v[202:205], v[96:99]
	v_mfma_f32_16x16x32_bf16 v[88:91], v[172:175], v[210:213], v[88:91]
	v_mfma_f32_16x16x32_bf16 v[80:83], v[180:183], v[210:213], v[80:83]
	v_mfma_f32_16x16x32_bf16 v[72:75], v[172:175], v[218:221], v[72:75]
	v_mfma_f32_16x16x32_bf16 v[64:67], v[180:183], v[218:221], v[64:67]
	s_setprio 0
	s_barrier
; #define PG8_STAGE(bufoff, gbase, voff) do { _Pragma("unroll") for (int _i = 0; _i < 2; ++_i) \
;         __builtin_amdgcn_global_load_lds((const unsigned*)((const char*)(gbase) + (voff)[_i]), (PG8_LAS unsigned*)(lds + (bufoff) + ldsw + _i * 8192), 16, 0, 0); } while (0)
; #define PG8_LDA(dst, b, h) do { _Pragma("unroll") for (int m = 0; m < 4; ++m) _Pragma("unroll") for (int k = 0; k < 2; ++k) dst[m][k] = *(const PG8_LAS bf16x8*)(lds + PG8_SA(b, h) + aoff + m * 2048 + k * 1024); } while (0)
; #define PG8_MMA(ai, bj, At, Bt) do { __builtin_amdgcn_s_setprio(1); _Pragma("unroll") for (int m = 0; m < 4; ++m) _Pragma("unroll") for (int n = 0; n < 2; ++n) _Pragma("unroll") for (int k = 0; k < 2; ++k) \
;         acc[ai][bj][m][n] = __builtin_amdgcn_mfma_f32_16x16x32_bf16(Bt[n][k], At[m][k], acc[ai][bj][m][n], 0, 0, 0); __builtin_amdgcn_s_setprio(0); } while (0)
; #define PG8_WAIT_V(n) asm volatile("s_waitcnt vmcnt(" #n ")" ::: "memory")
; #define PG8_WAIT_L(n) asm volatile("s_waitcnt lgkmcnt(" #n ")" ::: "memory")
; #define PG8_BAR __builtin_amdgcn_s_barrier()
; #define PG8_SCHED __builtin_amdgcn_sched_barrier(0)
; template <class Epi, class Sched, bool ALIGN_EPI = false, bool SP2 = false>
; __device__ __forceinline__ void gemm_phase(PG8_LAS unsigned char* lds, const Gemm g, const Sched S, const Epi E) {
;     ...
;         for (int t = 0; t < nt; t += 2) {
;             if constexpr (Epi::MIDT >= 0) { if (t == Epi::MIDT) E.mid(acc, cur, wr, fr); }
;             const bool last = (t == nt - 2);
;             const char* a1 = cA + (size_t)(t + 1) * kstep;
;             const char* a2 = last ? nA : cA + (size_t)(t + 2) * kstep; const char* b2 = last ? nB : cB + (size_t)(t + 2) * kstep;
;     ...
;             PG8_LDA(At, 1, 1); PG8_STAGE(PG8_SB(1, 0), b3, voffB); PG8_STAGE(PG8_SB(1, 1), b3 + hstep, voffB); PG8_STAGE(PG8_SA(1, 0), a3, voffA);
;             PG8_WAIT_V(8); PG8_WAIT_L(0); PG8_BAR; PG8_MMA(1, 0, At, B0); PG8_MMA(1, 1, At, B1); PG8_BAR; PG8_SCHED;
	s_add_i32 s50, s82, s8
	v_lshl_add_u64 v[144:145], v[144:145], 0, s[12:13]
	s_mov_b32 m0, s50
	ds_read_b128 v[190:193], v151 offset:49152
	ds_read_b128 v[194:197], v151 offset:50176
	ds_read_b128 v[198:201], v151 offset:51200
	ds_read_b128 v[202:205], v151 offset:52224
	ds_read_b128 v[206:209], v151 offset:53248
	ds_read_b128 v[210:213], v151 offset:54272
	ds_read_b128 v[214:217], v151 offset:55296
	ds_read_b128 v[218:221], v151 offset:56320
	global_load_lds_dwordx4 v[144:145], off
	s_add_i32 m0, s50, 0x2000
	s_add_u32 s44, s44, 0x40080
	v_lshl_add_u64 v[144:145], v[184:185], 0, s[12:13]
	s_addc_u32 s45, s45, 0
	s_add_i32 s50, s83, s8
	global_load_lds_dwordx4 v[144:145], off
	v_lshl_add_u64 v[144:145], s[44:45], 0, v[132:133]
	s_mov_b32 m0, s50
	s_nop 0
	global_load_lds_dwordx4 v[144:145], off
	v_lshl_add_u64 v[144:145], s[44:45], 0, v[128:129]
	s_add_i32 m0, s50, 0x2000
	s_nop 0
	global_load_lds_dwordx4 v[144:145], off
	v_lshl_add_u64 v[144:145], v[222:223], 0, s[12:13]
	s_mov_b32 m0, s49
	s_nop 0
	global_load_lds_dwordx4 v[144:145], off
	v_lshl_add_u64 v[144:145], v[224:225], 0, s[12:13]
	s_mov_b32 m0, s54
	s_nop 0
	global_load_lds_dwordx4 v[144:145], off
	s_waitcnt vmcnt(8)
	s_waitcnt lgkmcnt(0)
	s_barrier
	s_setprio 1
	s_waitcnt lgkmcnt(0)
	v_mfma_f32_16x16x32_bf16 v[60:63], v[152:155], v[190:193], v[60:63]
	v_mfma_f32_16x16x32_bf16 v[52:55], v[160:163], v[190:193], v[52:55]
	v_mfma_f32_16x16x32_bf16 v[44:47], v[152:155], v[198:201], v[44:47]
	v_mfma_f32_16x16x32_bf16 v[36:39], v[160:163], v[198:201], v[36:39]
	v_mfma_f32_16x16x32_bf16 v[28:31], v[152:155], v[206:209], v[28:31]
	v_mfma_f32_16x16x32_bf16 v[20:23], v[160:163], v[206:209], v[20:23]
	v_mfma_f32_16x16x32_bf16 v[12:15], v[152:155], v[214:217], v[12:15]
	v_mfma_f32_16x16x32_bf16 v[4:7], v[160:163], v[214:217], v[4:7]
	v_mfma_f32_16x16x32_bf16 v[60:63], v[156:159], v[194:197], v[60:63]
	v_mfma_f32_16x16x32_bf16 v[52:55], v[164:167], v[194:197], v[52:55]
	v_mfma_f32_16x16x32_bf16 v[44:47], v[156:159], v[202:205], v[44:47]
	v_mfma_f32_16x16x32_bf16 v[36:39], v[164:167], v[202:205], v[36:39]
	v_mfma_f32_16x16x32_bf16 v[28:31], v[156:159], v[210:213], v[28:31]
	v_mfma_f32_16x16x32_bf16 v[20:23], v[164:167], v[210:213], v[20:23]
	v_mfma_f32_16x16x32_bf16 v[12:15], v[156:159], v[218:221], v[12:15]
	v_mfma_f32_16x16x32_bf16 v[4:7], v[164:167], v[218:221], v[4:7]
	s_setprio 0
	s_setprio 1
	v_mfma_f32_16x16x32_bf16 v[56:59], v[168:171], v[190:193], v[56:59]
	v_mfma_f32_16x16x32_bf16 v[48:51], v[176:179], v[190:193], v[48:51]
	v_mfma_f32_16x16x32_bf16 v[40:43], v[168:171], v[198:201], v[40:43]
	v_mfma_f32_16x16x32_bf16 v[32:35], v[176:179], v[198:201], v[32:35]
	v_mfma_f32_16x16x32_bf16 v[24:27], v[168:171], v[206:209], v[24:27]
	v_mfma_f32_16x16x32_bf16 v[16:19], v[176:179], v[206:209], v[16:19]
	v_mfma_f32_16x16x32_bf16 v[8:11], v[168:171], v[214:217], v[8:11]
	v_mfma_f32_16x16x32_bf16 v[0:3], v[176:179], v[214:217], v[0:3]
	s_add_i32 s69, s69, 2
	s_add_u32 s42, s42, 0x100
	s_addc_u32 s43, s43, 0
	s_add_u32 s65, s65, 0x100
	s_addc_u32 s68, s68, 0
	s_cmp_gt_u32 s69, 13
	v_mfma_f32_16x16x32_bf16 v[56:59], v[172:175], v[194:197], v[56:59]
	v_mfma_f32_16x16x32_bf16 v[48:51], v[180:183], v[194:197], v[48:51]
	v_mfma_f32_16x16x32_bf16 v[40:43], v[172:175], v[202:205], v[40:43]
	v_mfma_f32_16x16x32_bf16 v[32:35], v[180:183], v[202:205], v[32:35]
	v_mfma_f32_16x16x32_bf16 v[24:27], v[172:175], v[210:213], v[24:27]
	v_mfma_f32_16x16x32_bf16 v[16:19], v[180:183], v[210:213], v[16:19]
	v_mfma_f32_16x16x32_bf16 v[8:11], v[172:175], v[218:221], v[8:11]
	v_mfma_f32_16x16x32_bf16 v[0:3], v[180:183], v[218:221], v[0:3]
	s_setprio 0
	s_barrier
	s_cbranch_scc0 .LBB0_276
	s_and_b64 vcc, exec, s[14:15]
	s_cbranch_vccz .LBB0_279
	s_barrier

; #define PG8_STAGE(bufoff, gbase, voff) do { _Pragma("unroll") for (int _i = 0; _i < 2; ++_i) \
;         __builtin_amdgcn_global_load_lds((const unsigned*)((const char*)(gbase) + (voff)[_i]), (PG8_LAS unsigned*)(lds + (bufoff) + ldsw + _i * 8192), 16, 0, 0); } while (0)
; #define PG8_LDA(dst, b, h) do { _Pragma("unroll") for (int m = 0; m < 4; ++m) _Pragma("unroll") for (int k = 0; k < 2; ++k) dst[m][k] = *(const PG8_LAS bf16x8*)(lds + PG8_SA(b, h) + aoff + m * 2048 + k * 1024); } while (0)
; #define PG8_LDB(dst, b, h) do { _Pragma("unroll") for (int n = 0; n < 2; ++n) _Pragma("unroll") for (int k = 0; k < 2; ++k) dst[n][k] = *(const PG8_LAS bf16x8*)(lds + PG8_SB(b, h) + boff + n * 2048 + k * 1024); } while (0)
; #define PG8_MMA(ai, bj, At, Bt) do { __builtin_amdgcn_s_setprio(1); _Pragma("unroll") for (int m = 0; m < 4; ++m) _Pragma("unroll") for (int n = 0; n < 2; ++n) _Pragma("unroll") for (int k = 0; k < 2; ++k) \
;         acc[ai][bj][m][n] = __builtin_amdgcn_mfma_f32_16x16x32_bf16(Bt[n][k], At[m][k], acc[ai][bj][m][n], 0, 0, 0); __builtin_amdgcn_s_setprio(0); } while (0)
; #define PG8_WAIT_V(n) asm volatile("s_waitcnt vmcnt(" #n ")" ::: "memory")
; #define PG8_WAIT_L(n) asm volatile("s_waitcnt lgkmcnt(" #n ")" ::: "memory")
; template <class Epi, class Sched, bool ALIGN_EPI = false, bool SP2 = false>
; __device__ __forceinline__ void gemm_phase(PG8_LAS unsigned char* lds, const Gemm g, const Sched S, const Epi E) {
;     ...
;             const bool last = (t == nt - 2);
;             const char* a1 = cA + (size_t)(t + 1) * kstep;
;             const char* a2 = last ? nA : cA + (size_t)(t + 2) * kstep; const char* b2 = last ? nB : cB + (size_t)(t + 2) * kstep;
;             const char* a3 = a2 + kstep; const char* b3 = b2 + kstep;
;             if (last && has_next) S.a_ready(nxt);
;             if constexpr (SP2) {
;             PG8_LDB(B0, 0, 0); PG8_LDB(B1, 0, 1); PG8_SCHED; PG8_LDA(At, 0, 0); PG8_STAGE(PG8_SA(1, 1), a1 + hstep, voffA);
;             PG8_WAIT_V(8); PG8_WAIT_L(0); PG8_BAR; PG8_MMA(0, 0, At, B0); PG8_MMA(0, 1, At, B1); PG8_BAR; PG8_SCHED;
;             PG8_LDA(At, 0, 1); PG8_STAGE(PG8_SB(0, 0), b2, voffB); PG8_STAGE(PG8_SB(0, 1), b2 + hstep, voffB); PG8_STAGE(PG8_SA(0, 0), a2, voffA);
;             PG8_WAIT_V(8); PG8_WAIT_L(0); PG8_BAR; PG8_MMA(1, 0, At, B0); PG8_MMA(1, 1, At, B1); PG8_BAR; PG8_SCHED;
.LBB0_356:
	ds_read_b128 v[144:147], v157
	ds_read_b128 v[148:151], v157 offset:1024
	ds_read_b128 v[160:163], v157 offset:2048
	ds_read_b128 v[164:167], v157 offset:3072
	ds_read_b128 v[168:171], v158
	ds_read_b128 v[172:175], v158 offset:1024
	ds_read_b128 v[176:179], v158 offset:2048
	ds_read_b128 v[180:183], v158 offset:3072
	s_add_u32 s40, s38, 0x100
	s_addc_u32 s41, s39, 0
	s_cmp_eq_u32 s65, 40
	s_cselect_b32 s45, s5, s41
	s_cselect_b32 s44, s4, s40
	s_cselect_b32 s43, s17, s64
	s_cselect_b32 s42, s16, s63
	v_lshl_add_u64 v[152:153], s[38:39], 0, v[136:137]
	s_add_i32 m0, s9, 0xc000
	ds_read_b128 v[190:193], v159
	ds_read_b128 v[194:197], v159 offset:1024
	ds_read_b128 v[198:201], v159 offset:2048
	ds_read_b128 v[202:205], v159 offset:3072
	ds_read_b128 v[206:209], v159 offset:4096
	ds_read_b128 v[210:213], v159 offset:5120
	ds_read_b128 v[214:217], v159 offset:6144
	ds_read_b128 v[218:221], v159 offset:7168
	global_load_lds_dwordx4 v[152:153], off
	v_lshl_add_u64 v[152:153], s[38:39], 0, v[138:139]
	s_add_i32 m0, s9, 0xe000
	s_nop 0
	global_load_lds_dwordx4 v[152:153], off
	s_waitcnt vmcnt(8)
	s_waitcnt lgkmcnt(0)
	s_barrier
	s_setprio 1
	s_waitcnt lgkmcnt(0)
	v_mfma_f32_16x16x32_bf16 v[124:127], v[144:147], v[190:193], v[124:127]
	v_mfma_f32_16x16x32_bf16 v[120:123], v[160:163], v[190:193], v[120:123]
	v_mfma_f32_16x16x32_bf16 v[108:111], v[144:147], v[198:201], v[108:111]
	v_mfma_f32_16x16x32_bf16 v[104:107], v[160:163], v[198:201], v[104:107]
	v_mfma_f32_16x16x32_bf16 v[92:95], v[144:147], v[206:209], v[92:95]
	v_mfma_f32_16x16x32_bf16 v[88:91], v[160:163], v[206:209], v[88:91]
	v_mfma_f32_16x16x32_bf16 v[76:79], v[144:147], v[214:217], v[76:79]
	v_mfma_f32_16x16x32_bf16 v[72:75], v[160:163], v[214:217], v[72:75]
	v_mfma_f32_16x16x32_bf16 v[124:127], v[148:151], v[194:197], v[124:127]
	v_mfma_f32_16x16x32_bf16 v[120:123], v[164:167], v[194:197], v[120:123]
	v_mfma_f32_16x16x32_bf16 v[108:111], v[148:151], v[202:205], v[108:111]
	v_mfma_f32_16x16x32_bf16 v[104:107], v[164:167], v[202:205], v[104:107]
	v_mfma_f32_16x16x32_bf16 v[92:95], v[148:151], v[210:213], v[92:95]
	v_mfma_f32_16x16x32_bf16 v[88:91], v[164:167], v[210:213], v[88:91]
	v_mfma_f32_16x16x32_bf16 v[76:79], v[148:151], v[218:221], v[76:79]
	v_mfma_f32_16x16x32_bf16 v[72:75], v[164:167], v[218:221], v[72:75]
	s_setprio 0
	s_setprio 1
	v_mfma_f32_16x16x32_bf16 v[116:119], v[168:171], v[190:193], v[116:119]
	v_mfma_f32_16x16x32_bf16 v[112:115], v[176:179], v[190:193], v[112:115]
	v_mfma_f32_16x16x32_bf16 v[100:103], v[168:171], v[198:201], v[100:103]
	v_mfma_f32_16x16x32_bf16 v[96:99], v[176:179], v[198:201], v[96:99]
	v_mfma_f32_16x16x32_bf16 v[84:87], v[168:171], v[206:209], v[84:87]
	v_mfma_f32_16x16x32_bf16 v[80:83], v[176:179], v[206:209], v[80:83]
	v_mfma_f32_16x16x32_bf16 v[68:71], v[168:171], v[214:217], v[68:71]
	v_mfma_f32_16x16x32_bf16 v[64:67], v[176:179], v[214:217], v[64:67]
	v_mfma_f32_16x16x32_bf16 v[116:119], v[172:175], v[194:197], v[116:119]
	v_mfma_f32_16x16x32_bf16 v[112:115], v[180:183], v[194:197], v[112:115]
	v_mfma_f32_16x16x32_bf16 v[100:103], v[172:175], v[202:205], v[100:103]
	v_mfma_f32_16x16x32_bf16 v[96:99], v[180:183], v[202:205], v[96:99]
	v_mfma_f32_16x16x32_bf16 v[84:87], v[172:175], v[210:213], v[84:87]
	v_mfma_f32_16x16x32_bf16 v[80:83], v[180:183], v[210:213], v[80:83]
	v_mfma_f32_16x16x32_bf16 v[68:71], v[172:175], v[218:221], v[68:71]
	v_mfma_f32_16x16x32_bf16 v[64:67], v[180:183], v[218:221], v[64:67]
	s_setprio 0
	s_barrier
	s_add_i32 s38, s55, s8
	v_lshl_add_u64 v[152:153], s[42:43], 0, v[130:131]
	s_mov_b32 m0, s38
	ds_read_b128 v[190:193], v159 offset:16384
	ds_read_b128 v[194:197], v159 offset:17408
	ds_read_b128 v[198:201], v159 offset:18432
	ds_read_b128 v[202:205], v159 offset:19456
	ds_read_b128 v[206:209], v159 offset:20480
	ds_read_b128 v[210:213], v159 offset:21504
	ds_read_b128 v[214:217], v159 offset:22528
	ds_read_b128 v[218:221], v159 offset:23552
	global_load_lds_dwordx4 v[152:153], off
	s_add_i32 m0, s38, 0x2000
	s_add_u32 s38, s42, 0xb0000
	v_lshl_add_u64 v[184:185], s[42:43], 0, v[134:135]
	s_addc_u32 s39, s43, 0
	s_add_i32 s68, s58, s8
	global_load_lds_dwordx4 v[184:185], off
	v_lshl_add_u64 v[222:223], s[38:39], 0, v[130:131]
	s_mov_b32 m0, s68
	v_lshl_add_u64 v[224:225], s[44:45], 0, v[132:133]
	global_load_lds_dwordx4 v[222:223], off
	v_lshl_add_u64 v[222:223], s[38:39], 0, v[134:135]
	s_add_i32 m0, s68, 0x2000
	s_nop 0
	global_load_lds_dwordx4 v[222:223], off
	v_lshl_add_u64 v[222:223], s[44:45], 0, v[128:129]
	s_mov_b32 m0, s9
	s_nop 0
	global_load_lds_dwordx4 v[222:223], off
	s_mov_b32 m0, s18
	s_nop 0
	global_load_lds_dwordx4 v[224:225], off
	s_waitcnt vmcnt(8)
	s_waitcnt lgkmcnt(0)
	s_barrier
; #define PG8_STAGE(bufoff, gbase, voff) do { _Pragma("unroll") for (int _i = 0; _i < 2; ++_i) \
;         __builtin_amdgcn_global_load_lds((const unsigned*)((const char*)(gbase) + (voff)[_i]), (PG8_LAS unsigned*)(lds + (bufoff) + ldsw + _i * 8192), 16, 0, 0); } while (0)
; #define PG8_LDA(dst, b, h) do { _Pragma("unroll") for (int m = 0; m < 4; ++m) _Pragma("unroll") for (int k = 0; k < 2; ++k) dst[m][k] = *(const PG8_LAS bf16x8*)(lds + PG8_SA(b, h) + aoff + m * 2048 + k * 1024); } while (0)
; #define PG8_LDB(dst, b, h) do { _Pragma("unroll") for (int n = 0; n < 2; ++n) _Pragma("unroll") for (int k = 0; k < 2; ++k) dst[n][k] = *(const PG8_LAS bf16x8*)(lds + PG8_SB(b, h) + boff + n * 2048 + k * 1024); } while (0)
; #define PG8_MMA(ai, bj, At, Bt) do { __builtin_amdgcn_s_setprio(1); _Pragma("unroll") for (int m = 0; m < 4; ++m) _Pragma("unroll") for (int n = 0; n < 2; ++n) _Pragma("unroll") for (int k = 0; k < 2; ++k) \
;         acc[ai][bj][m][n] = __builtin_amdgcn_mfma_f32_16x16x32_bf16(Bt[n][k], At[m][k], acc[ai][bj][m][n], 0, 0, 0); __builtin_amdgcn_s_setprio(0); } while (0)
; #define PG8_WAIT_V(n) asm volatile("s_waitcnt vmcnt(" #n ")" ::: "memory")
; #define PG8_WAIT_L(n) asm volatile("s_waitcnt lgkmcnt(" #n ")" ::: "memory")
; #define PG8_BAR __builtin_amdgcn_s_barrier()
; #define PG8_SCHED __builtin_amdgcn_sched_barrier(0)
; template <class Epi, class Sched, bool ALIGN_EPI = false, bool SP2 = false>
; __device__ __forceinline__ void gemm_phase(PG8_LAS unsigned char* lds, const Gemm g, const Sched S, const Epi E) {
;     ...
;             PG8_WAIT_V(8); PG8_WAIT_L(0); PG8_BAR; PG8_MMA(1, 0, At, B0); PG8_MMA(1, 1, At, B1); PG8_BAR; PG8_SCHED;
;             PG8_LDB(B0, 1, 0); PG8_LDB(B1, 1, 1); PG8_SCHED; PG8_LDA(At, 1, 0); PG8_STAGE(PG8_SA(0, 1), a2 + hstep, voffA);
;             PG8_WAIT_V(8); PG8_WAIT_L(0); PG8_BAR; PG8_MMA(0, 0, At, B0); PG8_MMA(0, 1, At, B1); PG8_BAR; PG8_SCHED;
	s_setprio 1
	s_waitcnt lgkmcnt(0)
	v_mfma_f32_16x16x32_bf16 v[60:63], v[144:147], v[190:193], v[60:63]
	v_mfma_f32_16x16x32_bf16 v[56:59], v[160:163], v[190:193], v[56:59]
	v_mfma_f32_16x16x32_bf16 v[44:47], v[144:147], v[198:201], v[44:47]
	v_mfma_f32_16x16x32_bf16 v[40:43], v[160:163], v[198:201], v[40:43]
	v_mfma_f32_16x16x32_bf16 v[28:31], v[144:147], v[206:209], v[28:31]
	v_mfma_f32_16x16x32_bf16 v[24:27], v[160:163], v[206:209], v[24:27]
	v_mfma_f32_16x16x32_bf16 v[12:15], v[144:147], v[214:217], v[12:15]
	v_mfma_f32_16x16x32_bf16 v[8:11], v[160:163], v[214:217], v[8:11]
	v_mfma_f32_16x16x32_bf16 v[60:63], v[148:151], v[194:197], v[60:63]
	v_mfma_f32_16x16x32_bf16 v[56:59], v[164:167], v[194:197], v[56:59]
	v_mfma_f32_16x16x32_bf16 v[44:47], v[148:151], v[202:205], v[44:47]
	v_mfma_f32_16x16x32_bf16 v[40:43], v[164:167], v[202:205], v[40:43]
	v_mfma_f32_16x16x32_bf16 v[28:31], v[148:151], v[210:213], v[28:31]
	v_mfma_f32_16x16x32_bf16 v[24:27], v[164:167], v[210:213], v[24:27]
	v_mfma_f32_16x16x32_bf16 v[12:15], v[148:151], v[218:221], v[12:15]
	v_mfma_f32_16x16x32_bf16 v[8:11], v[164:167], v[218:221], v[8:11]
	s_setprio 0
	s_setprio 1
	v_mfma_f32_16x16x32_bf16 v[52:55], v[168:171], v[190:193], v[52:55]
	v_mfma_f32_16x16x32_bf16 v[48:51], v[176:179], v[190:193], v[48:51]
	v_mfma_f32_16x16x32_bf16 v[36:39], v[168:171], v[198:201], v[36:39]
	v_mfma_f32_16x16x32_bf16 v[32:35], v[176:179], v[198:201], v[32:35]
	v_mfma_f32_16x16x32_bf16 v[20:23], v[168:171], v[206:209], v[20:23]
	v_mfma_f32_16x16x32_bf16 v[16:19], v[176:179], v[206:209], v[16:19]
	v_mfma_f32_16x16x32_bf16 v[4:7], v[168:171], v[214:217], v[4:7]
	v_mfma_f32_16x16x32_bf16 v[0:3], v[176:179], v[214:217], v[0:3]
	v_mfma_f32_16x16x32_bf16 v[52:55], v[172:175], v[194:197], v[52:55]
	v_mfma_f32_16x16x32_bf16 v[48:51], v[180:183], v[194:197], v[48:51]
	v_mfma_f32_16x16x32_bf16 v[36:39], v[172:175], v[202:205], v[36:39]
	v_mfma_f32_16x16x32_bf16 v[32:35], v[180:183], v[202:205], v[32:35]
	v_mfma_f32_16x16x32_bf16 v[20:23], v[172:175], v[210:213], v[20:23]
	v_mfma_f32_16x16x32_bf16 v[16:19], v[180:183], v[210:213], v[16:19]
	v_mfma_f32_16x16x32_bf16 v[4:7], v[172:175], v[218:221], v[4:7]
	v_mfma_f32_16x16x32_bf16 v[0:3], v[180:183], v[218:221], v[0:3]
	s_setprio 0
	s_barrier
	s_add_i32 s68, 0, 0x18000
	s_add_i32 s69, 0, 0x1c000
	v_add_u32_e32 v164, s68, v156
	v_add_u32_e32 v180, s69, v156
	ds_read_b128 v[144:147], v164
	ds_read_b128 v[148:151], v164 offset:1024
	ds_read_b128 v[160:163], v164 offset:2048
	ds_read_b128 v[164:167], v164 offset:3072
	ds_read_b128 v[168:171], v180
	ds_read_b128 v[172:175], v180 offset:1024
	ds_read_b128 v[176:179], v180 offset:2048
	ds_read_b128 v[180:183], v180 offset:3072
	s_add_u32 s38, s44, 0xb0000
	s_addc_u32 s39, s45, 0
	s_mov_b32 m0, s19
	v_lshl_add_u64 v[226:227], s[38:39], 0, v[128:129]
	ds_read_b128 v[190:193], v159 offset:32768
	ds_read_b128 v[194:197], v159 offset:33792
	ds_read_b128 v[198:201], v159 offset:34816
	ds_read_b128 v[202:205], v159 offset:35840
	ds_read_b128 v[206:209], v159 offset:36864
	ds_read_b128 v[210:213], v159 offset:37888
	ds_read_b128 v[214:217], v159 offset:38912
	ds_read_b128 v[218:221], v159 offset:39936
	global_load_lds_dwordx4 v[226:227], off
	v_lshl_add_u64 v[226:227], s[38:39], 0, v[132:133]
	s_mov_b32 m0, s33
	s_nop 0
	global_load_lds_dwordx4 v[226:227], off
	s_waitcnt vmcnt(8)
	s_waitcnt lgkmcnt(0)
	s_barrier
	s_setprio 1
	s_waitcnt lgkmcnt(0)
	v_mfma_f32_16x16x32_bf16 v[124:127], v[144:147], v[190:193], v[124:127]
	v_mfma_f32_16x16x32_bf16 v[120:123], v[160:163], v[190:193], v[120:123]
	v_mfma_f32_16x16x32_bf16 v[108:111], v[144:147], v[198:201], v[108:111]
	v_mfma_f32_16x16x32_bf16 v[104:107], v[160:163], v[198:201], v[104:107]
	v_mfma_f32_16x16x32_bf16 v[92:95], v[144:147], v[206:209], v[92:95]
	v_mfma_f32_16x16x32_bf16 v[88:91], v[160:163], v[206:209], v[88:91]
	v_mfma_f32_16x16x32_bf16 v[76:79], v[144:147], v[214:217], v[76:79]
	v_mfma_f32_16x16x32_bf16 v[72:75], v[160:163], v[214:217], v[72:75]
	v_mfma_f32_16x16x32_bf16 v[124:127], v[148:151], v[194:197], v[124:127]
	v_mfma_f32_16x16x32_bf16 v[120:123], v[164:167], v[194:197], v[120:123]
	v_mfma_f32_16x16x32_bf16 v[108:111], v[148:151], v[202:205], v[108:111]
	v_mfma_f32_16x16x32_bf16 v[104:107], v[164:167], v[202:205], v[104:107]
	v_mfma_f32_16x16x32_bf16 v[92:95], v[148:151], v[210:213], v[92:95]
	v_mfma_f32_16x16x32_bf16 v[88:91], v[164:167], v[210:213], v[88:91]
	v_mfma_f32_16x16x32_bf16 v[76:79], v[148:151], v[218:221], v[76:79]
	v_mfma_f32_16x16x32_bf16 v[72:75], v[164:167], v[218:221], v[72:75]
	s_setprio 0
	s_setprio 1
	v_mfma_f32_16x16x32_bf16 v[116:119], v[168:171], v[190:193], v[116:119]
	v_mfma_f32_16x16x32_bf16 v[112:115], v[176:179], v[190:193], v[112:115]
	v_mfma_f32_16x16x32_bf16 v[100:103], v[168:171], v[198:201], v[100:103]
	v_mfma_f32_16x16x32_bf16 v[96:99], v[176:179], v[198:201], v[96:99]
	v_mfma_f32_16x16x32_bf16 v[84:87], v[168:171], v[206:209], v[84:87]
	v_mfma_f32_16x16x32_bf16 v[80:83], v[176:179], v[206:209], v[80:83]
	v_mfma_f32_16x16x32_bf16 v[68:71], v[168:171], v[214:217], v[68:71]
	v_mfma_f32_16x16x32_bf16 v[64:67], v[176:179], v[214:217], v[64:67]
	v_mfma_f32_16x16x32_bf16 v[116:119], v[172:175], v[194:197], v[116:119]
	v_mfma_f32_16x16x32_bf16 v[112:115], v[180:183], v[194:197], v[112:115]
	v_mfma_f32_16x16x32_bf16 v[100:103], v[172:175], v[202:205], v[100:103]
	v_mfma_f32_16x16x32_bf16 v[96:99], v[180:183], v[202:205], v[96:99]
	v_mfma_f32_16x16x32_bf16 v[84:87], v[172:175], v[210:213], v[84:87]
	v_mfma_f32_16x16x32_bf16 v[80:83], v[180:183], v[210:213], v[80:83]
	v_mfma_f32_16x16x32_bf16 v[68:71], v[172:175], v[218:221], v[68:71]
	v_mfma_f32_16x16x32_bf16 v[64:67], v[180:183], v[218:221], v[64:67]
	s_setprio 0
	s_barrier
; #define PG8_STAGE(bufoff, gbase, voff) do { _Pragma("unroll") for (int _i = 0; _i < 2; ++_i) \
;         __builtin_amdgcn_global_load_lds((const unsigned*)((const char*)(gbase) + (voff)[_i]), (PG8_LAS unsigned*)(lds + (bufoff) + ldsw + _i * 8192), 16, 0, 0); } while (0)
; #define PG8_LDA(dst, b, h) do { _Pragma("unroll") for (int m = 0; m < 4; ++m) _Pragma("unroll") for (int k = 0; k < 2; ++k) dst[m][k] = *(const PG8_LAS bf16x8*)(lds + PG8_SA(b, h) + aoff + m * 2048 + k * 1024); } while (0)
; #define PG8_MMA(ai, bj, At, Bt) do { __builtin_amdgcn_s_setprio(1); _Pragma("unroll") for (int m = 0; m < 4; ++m) _Pragma("unroll") for (int n = 0; n < 2; ++n) _Pragma("unroll") for (int k = 0; k < 2; ++k) \
;         acc[ai][bj][m][n] = __builtin_amdgcn_mfma_f32_16x16x32_bf16(Bt[n][k], At[m][k], acc[ai][bj][m][n], 0, 0, 0); __builtin_amdgcn_s_setprio(0); } while (0)
; #define PG8_WAIT_V(n) asm volatile("s_waitcnt vmcnt(" #n ")" ::: "memory")
; #define PG8_WAIT_L(n) asm volatile("s_waitcnt lgkmcnt(" #n ")" ::: "memory")
; #define PG8_BAR __builtin_amdgcn_s_barrier()
; #define PG8_SCHED __builtin_amdgcn_sched_barrier(0)
; template <class Epi, class Sched, bool ALIGN_EPI = false, bool SP2 = false>
; __device__ __forceinline__ void gemm_phase(PG8_LAS unsigned char* lds, const Gemm g, const Sched S, const Epi E) {
;     ...
;         for (int t = 0; t < nt; t += 2) {
;             if constexpr (Epi::MIDT >= 0) { if (t == Epi::MIDT) E.mid(acc, cur, wr, fr); }
;             const bool last = (t == nt - 2);
;             const char* a1 = cA + (size_t)(t + 1) * kstep;
;             const char* a2 = last ? nA : cA + (size_t)(t + 2) * kstep; const char* b2 = last ? nB : cB + (size_t)(t + 2) * kstep;
;     ...
;             PG8_LDA(At, 1, 1); PG8_STAGE(PG8_SB(1, 0), b3, voffB); PG8_STAGE(PG8_SB(1, 1), b3 + hstep, voffB); PG8_STAGE(PG8_SA(1, 0), a3, voffA);
;             PG8_WAIT_V(8); PG8_WAIT_L(0); PG8_BAR; PG8_MMA(1, 0, At, B0); PG8_MMA(1, 1, At, B1); PG8_BAR; PG8_SCHED;
	s_add_i32 s38, s68, s8
	v_lshl_add_u64 v[152:153], v[152:153], 0, s[12:13]
	s_mov_b32 m0, s38
	ds_read_b128 v[190:193], v159 offset:49152
	ds_read_b128 v[194:197], v159 offset:50176
	ds_read_b128 v[198:201], v159 offset:51200
	ds_read_b128 v[202:205], v159 offset:52224
	ds_read_b128 v[206:209], v159 offset:53248
	ds_read_b128 v[210:213], v159 offset:54272
	ds_read_b128 v[214:217], v159 offset:55296
	ds_read_b128 v[218:221], v159 offset:56320
	global_load_lds_dwordx4 v[152:153], off
	s_add_i32 m0, s38, 0x2000
	s_add_u32 s38, s42, 0xb0080
	v_lshl_add_u64 v[152:153], v[184:185], 0, s[12:13]
	s_addc_u32 s39, s43, 0
	s_add_i32 s42, s69, s8
	global_load_lds_dwordx4 v[152:153], off
	v_lshl_add_u64 v[152:153], s[38:39], 0, v[130:131]
	s_mov_b32 m0, s42
	s_nop 0
	global_load_lds_dwordx4 v[152:153], off
	v_lshl_add_u64 v[152:153], s[38:39], 0, v[134:135]
	s_add_i32 m0, s42, 0x2000
	s_nop 0
	global_load_lds_dwordx4 v[152:153], off
	v_lshl_add_u64 v[152:153], v[222:223], 0, s[12:13]
	s_mov_b32 m0, s49
	s_nop 0
	global_load_lds_dwordx4 v[152:153], off
	v_lshl_add_u64 v[152:153], v[224:225], 0, s[12:13]
	s_mov_b32 m0, s50
	s_nop 0
	global_load_lds_dwordx4 v[152:153], off
	s_waitcnt vmcnt(8)
	s_waitcnt lgkmcnt(0)
	s_barrier
	s_setprio 1
	s_waitcnt lgkmcnt(0)
	v_mfma_f32_16x16x32_bf16 v[60:63], v[144:147], v[190:193], v[60:63]
	v_mfma_f32_16x16x32_bf16 v[56:59], v[160:163], v[190:193], v[56:59]
	v_mfma_f32_16x16x32_bf16 v[44:47], v[144:147], v[198:201], v[44:47]
	v_mfma_f32_16x16x32_bf16 v[40:43], v[160:163], v[198:201], v[40:43]
	v_mfma_f32_16x16x32_bf16 v[28:31], v[144:147], v[206:209], v[28:31]
	v_mfma_f32_16x16x32_bf16 v[24:27], v[160:163], v[206:209], v[24:27]
	v_mfma_f32_16x16x32_bf16 v[12:15], v[144:147], v[214:217], v[12:15]
	v_mfma_f32_16x16x32_bf16 v[8:11], v[160:163], v[214:217], v[8:11]
	v_mfma_f32_16x16x32_bf16 v[60:63], v[148:151], v[194:197], v[60:63]
	v_mfma_f32_16x16x32_bf16 v[56:59], v[164:167], v[194:197], v[56:59]
	v_mfma_f32_16x16x32_bf16 v[44:47], v[148:151], v[202:205], v[44:47]
	v_mfma_f32_16x16x32_bf16 v[40:43], v[164:167], v[202:205], v[40:43]
	v_mfma_f32_16x16x32_bf16 v[28:31], v[148:151], v[210:213], v[28:31]
	v_mfma_f32_16x16x32_bf16 v[24:27], v[164:167], v[210:213], v[24:27]
	v_mfma_f32_16x16x32_bf16 v[12:15], v[148:151], v[218:221], v[12:15]
	v_mfma_f32_16x16x32_bf16 v[8:11], v[164:167], v[218:221], v[8:11]
	s_setprio 0
	s_setprio 1
	v_mfma_f32_16x16x32_bf16 v[52:55], v[168:171], v[190:193], v[52:55]
	v_mfma_f32_16x16x32_bf16 v[48:51], v[176:179], v[190:193], v[48:51]
	v_mfma_f32_16x16x32_bf16 v[36:39], v[168:171], v[198:201], v[36:39]
	v_mfma_f32_16x16x32_bf16 v[32:35], v[176:179], v[198:201], v[32:35]
	v_mfma_f32_16x16x32_bf16 v[20:23], v[168:171], v[206:209], v[20:23]
	v_mfma_f32_16x16x32_bf16 v[16:19], v[176:179], v[206:209], v[16:19]
	v_mfma_f32_16x16x32_bf16 v[4:7], v[168:171], v[214:217], v[4:7]
	v_mfma_f32_16x16x32_bf16 v[0:3], v[176:179], v[214:217], v[0:3]
	s_add_i32 s65, s65, 2
	s_add_u32 s63, s63, 0x100
	s_addc_u32 s64, s64, 0
	s_cmp_gt_u32 s65, 41
	s_mov_b64 s[38:39], s[40:41]
	v_mfma_f32_16x16x32_bf16 v[52:55], v[172:175], v[194:197], v[52:55]
	v_mfma_f32_16x16x32_bf16 v[48:51], v[180:183], v[194:197], v[48:51]
	v_mfma_f32_16x16x32_bf16 v[36:39], v[172:175], v[202:205], v[36:39]
	v_mfma_f32_16x16x32_bf16 v[32:35], v[180:183], v[202:205], v[32:35]
	v_mfma_f32_16x16x32_bf16 v[20:23], v[172:175], v[210:213], v[20:23]
	v_mfma_f32_16x16x32_bf16 v[16:19], v[180:183], v[210:213], v[16:19]
	v_mfma_f32_16x16x32_bf16 v[4:7], v[172:175], v[218:221], v[4:7]
	v_mfma_f32_16x16x32_bf16 v[0:3], v[180:183], v[218:221], v[0:3]
	s_setprio 0
	s_barrier
	s_cbranch_scc0 .LBB0_356
	s_and_b64 vcc, exec, s[14:15]
	s_cbranch_vccz .LBB0_359
	s_barrier

; #define PG8_STAGE(bufoff, gbase, voff) do { _Pragma("unroll") for (int _i = 0; _i < 2; ++_i) \
;         __builtin_amdgcn_global_load_lds((const unsigned*)((const char*)(gbase) + (voff)[_i]), (PG8_LAS unsigned*)(lds + (bufoff) + ldsw + _i * 8192), 16, 0, 0); } while (0)
; #define PG8_LDA(dst, b, h) do { _Pragma("unroll") for (int m = 0; m < 4; ++m) _Pragma("unroll") for (int k = 0; k < 2; ++k) dst[m][k] = *(const PG8_LAS bf16x8*)(lds + PG8_SA(b, h) + aoff + m * 2048 + k * 1024); } while (0)
; #define PG8_LDB(dst, b, h) do { _Pragma("unroll") for (int n = 0; n < 2; ++n) _Pragma("unroll") for (int k = 0; k < 2; ++k) dst[n][k] = *(const PG8_LAS bf16x8*)(lds + PG8_SB(b, h) + boff + n * 2048 + k * 1024); } while (0)
; #define PG8_MMA(ai, bj, At, Bt) do { __builtin_amdgcn_s_setprio(1); _Pragma("unroll") for (int m = 0; m < 4; ++m) _Pragma("unroll") for (int n = 0; n < 2; ++n) _Pragma("unroll") for (int k = 0; k < 2; ++k) \
;         acc[ai][bj][m][n] = __builtin_amdgcn_mfma_f32_16x16x32_bf16(Bt[n][k], At[m][k], acc[ai][bj][m][n], 0, 0, 0); __builtin_amdgcn_s_setprio(0); } while (0)
; #define PG8_WAIT_V(n) asm volatile("s_waitcnt vmcnt(" #n ")" ::: "memory")
; #define PG8_WAIT_L(n) asm volatile("s_waitcnt lgkmcnt(" #n ")" ::: "memory")
; template <class Epi, class Sched, bool ALIGN_EPI = false, bool SP2 = false>
; __device__ __forceinline__ void gemm_phase(PG8_LAS unsigned char* lds, const Gemm g, const Sched S, const Epi E) {
;     ...
;             const bool last = (t == nt - 2);
;             const char* a1 = cA + (size_t)(t + 1) * kstep;
;             const char* a2 = last ? nA : cA + (size_t)(t + 2) * kstep; const char* b2 = last ? nB : cB + (size_t)(t + 2) * kstep;
;             const char* a3 = a2 + kstep; const char* b3 = b2 + kstep;
;             if (last && has_next) S.a_ready(nxt);
;             if constexpr (SP2) {
;             PG8_LDB(B0, 0, 0); PG8_LDB(B1, 0, 1); PG8_SCHED; PG8_LDA(At, 0, 0); PG8_STAGE(PG8_SA(1, 1), a1 + hstep, voffA);
;             PG8_WAIT_V(8); PG8_WAIT_L(0); PG8_BAR; PG8_MMA(0, 0, At, B0); PG8_MMA(0, 1, At, B1); PG8_BAR; PG8_SCHED;
;             PG8_LDA(At, 0, 1); PG8_STAGE(PG8_SB(0, 0), b2, voffB); PG8_STAGE(PG8_SB(0, 1), b2 + hstep, voffB); PG8_STAGE(PG8_SA(0, 0), a2, voffA);
;             PG8_WAIT_V(8); PG8_WAIT_L(0); PG8_BAR; PG8_MMA(1, 0, At, B0); PG8_MMA(1, 1, At, B1); PG8_BAR; PG8_SCHED;
.LBB0_484:
	ds_read_b128 v[128:131], v193
	ds_read_b128 v[132:135], v193 offset:1024
	ds_read_b128 v[150:153], v193 offset:2048
	ds_read_b128 v[154:157], v193 offset:3072
	ds_read_b128 v[158:161], v194
	ds_read_b128 v[162:165], v194 offset:1024
	ds_read_b128 v[166:169], v194 offset:2048
	ds_read_b128 v[170:173], v194 offset:3072
	s_add_u32 s10, s6, 0xfffc0080
	s_addc_u32 s11, s7, -1
	s_cmp_eq_u32 s61, 12
	s_cselect_b32 s93, s1, s11
	s_cselect_b32 s92, s33, s10
	s_cselect_b32 s11, s36, s60
	s_cselect_b32 s10, s58, s59
	v_lshl_add_u64 v[220:221], s[6:7], 0, v[142:143]
	s_add_i32 m0, s19, 0xc000
	ds_read_b128 v[174:177], v195
	ds_read_b128 v[178:181], v195 offset:1024
	ds_read_b128 v[182:185], v195 offset:2048
	ds_read_b128 v[200:203], v195 offset:3072
	ds_read_b128 v[204:207], v195 offset:4096
	ds_read_b128 v[208:211], v195 offset:5120
	ds_read_b128 v[212:215], v195 offset:6144
	ds_read_b128 v[216:219], v195 offset:7168
	global_load_lds_dwordx4 v[220:221], off
	v_lshl_add_u64 v[220:221], s[6:7], 0, v[144:145]
	s_add_i32 m0, s19, 0xe000
	s_nop 0
	global_load_lds_dwordx4 v[220:221], off
	s_waitcnt vmcnt(8)
	s_waitcnt lgkmcnt(0)
	s_barrier
	s_setprio 1
	s_waitcnt lgkmcnt(0)
	v_mfma_f32_16x16x32_bf16 v[124:127], v[128:131], v[174:177], v[124:127]
	v_mfma_f32_16x16x32_bf16 v[120:123], v[150:153], v[174:177], v[120:123]
	v_mfma_f32_16x16x32_bf16 v[108:111], v[128:131], v[182:185], v[108:111]
	v_mfma_f32_16x16x32_bf16 v[104:107], v[150:153], v[182:185], v[104:107]
	v_mfma_f32_16x16x32_bf16 v[92:95], v[128:131], v[204:207], v[92:95]
	v_mfma_f32_16x16x32_bf16 v[88:91], v[150:153], v[204:207], v[88:91]
	v_mfma_f32_16x16x32_bf16 v[76:79], v[128:131], v[212:215], v[76:79]
	v_mfma_f32_16x16x32_bf16 v[72:75], v[150:153], v[212:215], v[72:75]
	v_mfma_f32_16x16x32_bf16 v[124:127], v[132:135], v[178:181], v[124:127]
	v_mfma_f32_16x16x32_bf16 v[120:123], v[154:157], v[178:181], v[120:123]
	v_mfma_f32_16x16x32_bf16 v[108:111], v[132:135], v[200:203], v[108:111]
	v_mfma_f32_16x16x32_bf16 v[104:107], v[154:157], v[200:203], v[104:107]
	v_mfma_f32_16x16x32_bf16 v[92:95], v[132:135], v[208:211], v[92:95]
	v_mfma_f32_16x16x32_bf16 v[88:91], v[154:157], v[208:211], v[88:91]
	v_mfma_f32_16x16x32_bf16 v[76:79], v[132:135], v[216:219], v[76:79]
	v_mfma_f32_16x16x32_bf16 v[72:75], v[154:157], v[216:219], v[72:75]
	s_setprio 0
	s_setprio 1
	v_mfma_f32_16x16x32_bf16 v[116:119], v[158:161], v[174:177], v[116:119]
	v_mfma_f32_16x16x32_bf16 v[112:115], v[166:169], v[174:177], v[112:115]
	v_mfma_f32_16x16x32_bf16 v[100:103], v[158:161], v[182:185], v[100:103]
	v_mfma_f32_16x16x32_bf16 v[96:99], v[166:169], v[182:185], v[96:99]
	v_mfma_f32_16x16x32_bf16 v[84:87], v[158:161], v[204:207], v[84:87]
	v_mfma_f32_16x16x32_bf16 v[80:83], v[166:169], v[204:207], v[80:83]
	v_mfma_f32_16x16x32_bf16 v[68:71], v[158:161], v[212:215], v[68:71]
	v_mfma_f32_16x16x32_bf16 v[64:67], v[166:169], v[212:215], v[64:67]
	v_mfma_f32_16x16x32_bf16 v[116:119], v[162:165], v[178:181], v[116:119]
	v_mfma_f32_16x16x32_bf16 v[112:115], v[170:173], v[178:181], v[112:115]
	v_mfma_f32_16x16x32_bf16 v[100:103], v[162:165], v[200:203], v[100:103]
	v_mfma_f32_16x16x32_bf16 v[96:99], v[170:173], v[200:203], v[96:99]
	v_mfma_f32_16x16x32_bf16 v[84:87], v[162:165], v[208:211], v[84:87]
	v_mfma_f32_16x16x32_bf16 v[80:83], v[170:173], v[208:211], v[80:83]
	v_mfma_f32_16x16x32_bf16 v[68:71], v[162:165], v[216:219], v[68:71]
	v_mfma_f32_16x16x32_bf16 v[64:67], v[170:173], v[216:219], v[64:67]
	s_setprio 0
	s_barrier
	s_add_i32 s85, s65, s18
	v_lshl_add_u64 v[220:221], s[10:11], 0, v[136:137]
	s_mov_b32 m0, s85
	ds_read_b128 v[174:177], v195 offset:16384
	ds_read_b128 v[178:181], v195 offset:17408
	ds_read_b128 v[182:185], v195 offset:18432
	ds_read_b128 v[200:203], v195 offset:19456
	ds_read_b128 v[204:207], v195 offset:20480
	ds_read_b128 v[208:211], v195 offset:21504
	ds_read_b128 v[212:215], v195 offset:22528
	ds_read_b128 v[216:219], v195 offset:23552
	global_load_lds_dwordx4 v[220:221], off
	s_add_i32 m0, s85, 0x2000
	s_add_u32 s96, s10, 0x40000
	v_lshl_add_u64 v[222:223], s[10:11], 0, v[138:139]
	s_addc_u32 s97, s11, 0
	s_add_i32 s85, s46, s18
	global_load_lds_dwordx4 v[222:223], off
	v_lshl_add_u64 v[224:225], s[96:97], 0, v[136:137]
	s_mov_b32 m0, s85
	v_lshl_add_u64 v[226:227], s[92:93], 0, v[138:139]
	global_load_lds_dwordx4 v[224:225], off
	v_lshl_add_u64 v[224:225], s[96:97], 0, v[138:139]
	s_add_i32 m0, s85, 0x2000
	s_nop 0
	global_load_lds_dwordx4 v[224:225], off
	v_lshl_add_u64 v[224:225], s[92:93], 0, v[136:137]
	s_mov_b32 m0, s19
	s_nop 0
	global_load_lds_dwordx4 v[224:225], off
	s_mov_b32 m0, s95
	s_nop 0
	global_load_lds_dwordx4 v[226:227], off
	s_waitcnt vmcnt(8)
	s_waitcnt lgkmcnt(0)
	s_barrier
; #define PG8_STAGE(bufoff, gbase, voff) do { _Pragma("unroll") for (int _i = 0; _i < 2; ++_i) \
;         __builtin_amdgcn_global_load_lds((const unsigned*)((const char*)(gbase) + (voff)[_i]), (PG8_LAS unsigned*)(lds + (bufoff) + ldsw + _i * 8192), 16, 0, 0); } while (0)
; #define PG8_LDA(dst, b, h) do { _Pragma("unroll") for (int m = 0; m < 4; ++m) _Pragma("unroll") for (int k = 0; k < 2; ++k) dst[m][k] = *(const PG8_LAS bf16x8*)(lds + PG8_SA(b, h) + aoff + m * 2048 + k * 1024); } while (0)
; #define PG8_LDB(dst, b, h) do { _Pragma("unroll") for (int n = 0; n < 2; ++n) _Pragma("unroll") for (int k = 0; k < 2; ++k) dst[n][k] = *(const PG8_LAS bf16x8*)(lds + PG8_SB(b, h) + boff + n * 2048 + k * 1024); } while (0)
; #define PG8_MMA(ai, bj, At, Bt) do { __builtin_amdgcn_s_setprio(1); _Pragma("unroll") for (int m = 0; m < 4; ++m) _Pragma("unroll") for (int n = 0; n < 2; ++n) _Pragma("unroll") for (int k = 0; k < 2; ++k) \
;         acc[ai][bj][m][n] = __builtin_amdgcn_mfma_f32_16x16x32_bf16(Bt[n][k], At[m][k], acc[ai][bj][m][n], 0, 0, 0); __builtin_amdgcn_s_setprio(0); } while (0)
; #define PG8_WAIT_V(n) asm volatile("s_waitcnt vmcnt(" #n ")" ::: "memory")
; #define PG8_WAIT_L(n) asm volatile("s_waitcnt lgkmcnt(" #n ")" ::: "memory")
; #define PG8_BAR __builtin_amdgcn_s_barrier()
; #define PG8_SCHED __builtin_amdgcn_sched_barrier(0)
; template <class Epi, class Sched, bool ALIGN_EPI = false, bool SP2 = false>
; __device__ __forceinline__ void gemm_phase(PG8_LAS unsigned char* lds, const Gemm g, const Sched S, const Epi E) {
;     ...
;             PG8_WAIT_V(8); PG8_WAIT_L(0); PG8_BAR; PG8_MMA(1, 0, At, B0); PG8_MMA(1, 1, At, B1); PG8_BAR; PG8_SCHED;
;             PG8_LDB(B0, 1, 0); PG8_LDB(B1, 1, 1); PG8_SCHED; PG8_LDA(At, 1, 0); PG8_STAGE(PG8_SA(0, 1), a2 + hstep, voffA);
;             PG8_WAIT_V(8); PG8_WAIT_L(0); PG8_BAR; PG8_MMA(0, 0, At, B0); PG8_MMA(0, 1, At, B1); PG8_BAR; PG8_SCHED;
	s_setprio 1
	s_waitcnt lgkmcnt(0)
	v_mfma_f32_16x16x32_bf16 v[60:63], v[128:131], v[174:177], v[60:63]
	v_mfma_f32_16x16x32_bf16 v[56:59], v[150:153], v[174:177], v[56:59]
	v_mfma_f32_16x16x32_bf16 v[44:47], v[128:131], v[182:185], v[44:47]
	v_mfma_f32_16x16x32_bf16 v[40:43], v[150:153], v[182:185], v[40:43]
	v_mfma_f32_16x16x32_bf16 v[28:31], v[128:131], v[204:207], v[28:31]
	v_mfma_f32_16x16x32_bf16 v[24:27], v[150:153], v[204:207], v[24:27]
	v_mfma_f32_16x16x32_bf16 v[12:15], v[128:131], v[212:215], v[12:15]
	v_mfma_f32_16x16x32_bf16 v[8:11], v[150:153], v[212:215], v[8:11]
	v_mfma_f32_16x16x32_bf16 v[60:63], v[132:135], v[178:181], v[60:63]
	v_mfma_f32_16x16x32_bf16 v[56:59], v[154:157], v[178:181], v[56:59]
	v_mfma_f32_16x16x32_bf16 v[44:47], v[132:135], v[200:203], v[44:47]
	v_mfma_f32_16x16x32_bf16 v[40:43], v[154:157], v[200:203], v[40:43]
	v_mfma_f32_16x16x32_bf16 v[28:31], v[132:135], v[208:211], v[28:31]
	v_mfma_f32_16x16x32_bf16 v[24:27], v[154:157], v[208:211], v[24:27]
	v_mfma_f32_16x16x32_bf16 v[12:15], v[132:135], v[216:219], v[12:15]
	v_mfma_f32_16x16x32_bf16 v[8:11], v[154:157], v[216:219], v[8:11]
	s_setprio 0
	s_setprio 1
	v_mfma_f32_16x16x32_bf16 v[52:55], v[158:161], v[174:177], v[52:55]
	v_mfma_f32_16x16x32_bf16 v[48:51], v[166:169], v[174:177], v[48:51]
	v_mfma_f32_16x16x32_bf16 v[36:39], v[158:161], v[182:185], v[36:39]
	v_mfma_f32_16x16x32_bf16 v[32:35], v[166:169], v[182:185], v[32:35]
	v_mfma_f32_16x16x32_bf16 v[20:23], v[158:161], v[204:207], v[20:23]
	v_mfma_f32_16x16x32_bf16 v[16:19], v[166:169], v[204:207], v[16:19]
	v_mfma_f32_16x16x32_bf16 v[4:7], v[158:161], v[212:215], v[4:7]
	v_mfma_f32_16x16x32_bf16 v[0:3], v[166:169], v[212:215], v[0:3]
	v_mfma_f32_16x16x32_bf16 v[52:55], v[162:165], v[178:181], v[52:55]
	v_mfma_f32_16x16x32_bf16 v[48:51], v[170:173], v[178:181], v[48:51]
	v_mfma_f32_16x16x32_bf16 v[36:39], v[162:165], v[200:203], v[36:39]
	v_mfma_f32_16x16x32_bf16 v[32:35], v[170:173], v[200:203], v[32:35]
	v_mfma_f32_16x16x32_bf16 v[20:23], v[162:165], v[208:211], v[20:23]
	v_mfma_f32_16x16x32_bf16 v[16:19], v[170:173], v[208:211], v[16:19]
	v_mfma_f32_16x16x32_bf16 v[4:7], v[162:165], v[216:219], v[4:7]
	v_mfma_f32_16x16x32_bf16 v[0:3], v[170:173], v[216:219], v[0:3]
	s_setprio 0
	s_barrier
	s_add_i32 s85, 0, 0x18000
	v_add_u32_e32 v140, s85, v191
	s_add_i32 s87, 0, 0x1c000
	ds_read_b128 v[128:131], v140
	ds_read_b128 v[132:135], v140 offset:1024
	ds_read_b128 v[150:153], v140 offset:2048
	ds_read_b128 v[154:157], v140 offset:3072
	v_add_u32_e32 v140, s87, v191
	ds_read_b128 v[158:161], v140
	ds_read_b128 v[162:165], v140 offset:1024
	ds_read_b128 v[166:169], v140 offset:2048
	ds_read_b128 v[170:173], v140 offset:3072
	s_add_u32 s92, s92, 0x40000
	s_addc_u32 s93, s93, 0
	s_mov_b32 m0, s8
	v_lshl_add_u64 v[228:229], s[92:93], 0, v[136:137]
	ds_read_b128 v[174:177], v195 offset:32768
	ds_read_b128 v[178:181], v195 offset:33792
	ds_read_b128 v[182:185], v195 offset:34816
	ds_read_b128 v[200:203], v195 offset:35840
	ds_read_b128 v[204:207], v195 offset:36864
	ds_read_b128 v[208:211], v195 offset:37888
	ds_read_b128 v[212:215], v195 offset:38912
	ds_read_b128 v[216:219], v195 offset:39936
	global_load_lds_dwordx4 v[228:229], off
	v_lshl_add_u64 v[228:229], s[92:93], 0, v[138:139]
	s_mov_b32 m0, s9
	s_nop 0
	global_load_lds_dwordx4 v[228:229], off
	s_waitcnt vmcnt(8)
	s_waitcnt lgkmcnt(0)
	s_barrier
	s_setprio 1
	s_waitcnt lgkmcnt(0)
	v_mfma_f32_16x16x32_bf16 v[124:127], v[128:131], v[174:177], v[124:127]
	v_mfma_f32_16x16x32_bf16 v[120:123], v[150:153], v[174:177], v[120:123]
	v_mfma_f32_16x16x32_bf16 v[108:111], v[128:131], v[182:185], v[108:111]
	v_mfma_f32_16x16x32_bf16 v[104:107], v[150:153], v[182:185], v[104:107]
	v_mfma_f32_16x16x32_bf16 v[92:95], v[128:131], v[204:207], v[92:95]
	v_mfma_f32_16x16x32_bf16 v[88:91], v[150:153], v[204:207], v[88:91]
	v_mfma_f32_16x16x32_bf16 v[76:79], v[128:131], v[212:215], v[76:79]
	v_mfma_f32_16x16x32_bf16 v[72:75], v[150:153], v[212:215], v[72:75]
	v_mfma_f32_16x16x32_bf16 v[124:127], v[132:135], v[178:181], v[124:127]
	v_mfma_f32_16x16x32_bf16 v[120:123], v[154:157], v[178:181], v[120:123]
	v_mfma_f32_16x16x32_bf16 v[108:111], v[132:135], v[200:203], v[108:111]
	v_mfma_f32_16x16x32_bf16 v[104:107], v[154:157], v[200:203], v[104:107]
	v_mfma_f32_16x16x32_bf16 v[92:95], v[132:135], v[208:211], v[92:95]
	v_mfma_f32_16x16x32_bf16 v[88:91], v[154:157], v[208:211], v[88:91]
	v_mfma_f32_16x16x32_bf16 v[76:79], v[132:135], v[216:219], v[76:79]
	v_mfma_f32_16x16x32_bf16 v[72:75], v[154:157], v[216:219], v[72:75]
	s_setprio 0
	s_setprio 1
	v_mfma_f32_16x16x32_bf16 v[116:119], v[158:161], v[174:177], v[116:119]
	v_mfma_f32_16x16x32_bf16 v[112:115], v[166:169], v[174:177], v[112:115]
	v_mfma_f32_16x16x32_bf16 v[100:103], v[158:161], v[182:185], v[100:103]
	v_mfma_f32_16x16x32_bf16 v[96:99], v[166:169], v[182:185], v[96:99]
	v_mfma_f32_16x16x32_bf16 v[84:87], v[158:161], v[204:207], v[84:87]
	v_mfma_f32_16x16x32_bf16 v[80:83], v[166:169], v[204:207], v[80:83]
	v_mfma_f32_16x16x32_bf16 v[68:71], v[158:161], v[212:215], v[68:71]
	v_mfma_f32_16x16x32_bf16 v[64:67], v[166:169], v[212:215], v[64:67]
	v_mfma_f32_16x16x32_bf16 v[116:119], v[162:165], v[178:181], v[116:119]
	v_mfma_f32_16x16x32_bf16 v[112:115], v[170:173], v[178:181], v[112:115]
	v_mfma_f32_16x16x32_bf16 v[100:103], v[162:165], v[200:203], v[100:103]
	v_mfma_f32_16x16x32_bf16 v[96:99], v[170:173], v[200:203], v[96:99]
	v_mfma_f32_16x16x32_bf16 v[84:87], v[162:165], v[208:211], v[84:87]
	v_mfma_f32_16x16x32_bf16 v[80:83], v[170:173], v[208:211], v[80:83]
	v_mfma_f32_16x16x32_bf16 v[68:71], v[162:165], v[216:219], v[68:71]
	v_mfma_f32_16x16x32_bf16 v[64:67], v[170:173], v[216:219], v[64:67]
	s_setprio 0
	s_barrier
; #define PG8_STAGE(bufoff, gbase, voff) do { _Pragma("unroll") for (int _i = 0; _i < 2; ++_i) \
;         __builtin_amdgcn_global_load_lds((const unsigned*)((const char*)(gbase) + (voff)[_i]), (PG8_LAS unsigned*)(lds + (bufoff) + ldsw + _i * 8192), 16, 0, 0); } while (0)
; #define PG8_LDA(dst, b, h) do { _Pragma("unroll") for (int m = 0; m < 4; ++m) _Pragma("unroll") for (int k = 0; k < 2; ++k) dst[m][k] = *(const PG8_LAS bf16x8*)(lds + PG8_SA(b, h) + aoff + m * 2048 + k * 1024); } while (0)
; #define PG8_MMA(ai, bj, At, Bt) do { __builtin_amdgcn_s_setprio(1); _Pragma("unroll") for (int m = 0; m < 4; ++m) _Pragma("unroll") for (int n = 0; n < 2; ++n) _Pragma("unroll") for (int k = 0; k < 2; ++k) \
;         acc[ai][bj][m][n] = __builtin_amdgcn_mfma_f32_16x16x32_bf16(Bt[n][k], At[m][k], acc[ai][bj][m][n], 0, 0, 0); __builtin_amdgcn_s_setprio(0); } while (0)
; #define PG8_WAIT_V(n) asm volatile("s_waitcnt vmcnt(" #n ")" ::: "memory")
; #define PG8_WAIT_L(n) asm volatile("s_waitcnt lgkmcnt(" #n ")" ::: "memory")
; #define PG8_BAR __builtin_amdgcn_s_barrier()
; #define PG8_SCHED __builtin_amdgcn_sched_barrier(0)
; template <class Epi, class Sched, bool ALIGN_EPI = false, bool SP2 = false>
; __device__ __forceinline__ void gemm_phase(PG8_LAS unsigned char* lds, const Gemm g, const Sched S, const Epi E) {
;     ...
;         for (int t = 0; t < nt; t += 2) {
;             if constexpr (Epi::MIDT >= 0) { if (t == Epi::MIDT) E.mid(acc, cur, wr, fr); }
;             const bool last = (t == nt - 2);
;             const char* a1 = cA + (size_t)(t + 1) * kstep;
;             const char* a2 = last ? nA : cA + (size_t)(t + 2) * kstep; const char* b2 = last ? nB : cB + (size_t)(t + 2) * kstep;
;     ...
;             PG8_LDA(At, 1, 1); PG8_STAGE(PG8_SB(1, 0), b3, voffB); PG8_STAGE(PG8_SB(1, 1), b3 + hstep, voffB); PG8_STAGE(PG8_SA(1, 0), a3, voffA);
;             PG8_WAIT_V(8); PG8_WAIT_L(0); PG8_BAR; PG8_MMA(1, 0, At, B0); PG8_MMA(1, 1, At, B1); PG8_BAR; PG8_SCHED;
	s_add_i32 s85, s85, s18
	v_lshl_add_u64 v[220:221], v[220:221], 0, s[52:53]
	s_mov_b32 m0, s85
	ds_read_b128 v[174:177], v195 offset:49152
	ds_read_b128 v[178:181], v195 offset:50176
	ds_read_b128 v[182:185], v195 offset:51200
	ds_read_b128 v[200:203], v195 offset:52224
	ds_read_b128 v[204:207], v195 offset:53248
	ds_read_b128 v[208:211], v195 offset:54272
	ds_read_b128 v[212:215], v195 offset:55296
	ds_read_b128 v[216:219], v195 offset:56320
	global_load_lds_dwordx4 v[220:221], off
	s_add_i32 m0, s85, 0x2000
	s_add_u32 s10, s10, 0x40080
	v_lshl_add_u64 v[220:221], v[222:223], 0, s[52:53]
	s_addc_u32 s11, s11, 0
	s_add_i32 s85, s87, s18
	global_load_lds_dwordx4 v[220:221], off
	v_lshl_add_u64 v[220:221], s[10:11], 0, v[136:137]
	s_mov_b32 m0, s85
	s_nop 0
	global_load_lds_dwordx4 v[220:221], off
	v_lshl_add_u64 v[220:221], s[10:11], 0, v[138:139]
	s_add_i32 m0, s85, 0x2000
	s_nop 0
	global_load_lds_dwordx4 v[220:221], off
	v_lshl_add_u64 v[220:221], v[224:225], 0, s[52:53]
	s_mov_b32 m0, s67
	s_nop 0
	global_load_lds_dwordx4 v[220:221], off
	v_lshl_add_u64 v[220:221], v[226:227], 0, s[52:53]
	s_mov_b32 m0, s54
	s_nop 0
	global_load_lds_dwordx4 v[220:221], off
	s_waitcnt vmcnt(8)
	s_waitcnt lgkmcnt(0)
	s_barrier
	s_setprio 1
	s_waitcnt lgkmcnt(0)
	v_mfma_f32_16x16x32_bf16 v[60:63], v[128:131], v[174:177], v[60:63]
	v_mfma_f32_16x16x32_bf16 v[56:59], v[150:153], v[174:177], v[56:59]
	v_mfma_f32_16x16x32_bf16 v[44:47], v[128:131], v[182:185], v[44:47]
	v_mfma_f32_16x16x32_bf16 v[40:43], v[150:153], v[182:185], v[40:43]
	v_mfma_f32_16x16x32_bf16 v[28:31], v[128:131], v[204:207], v[28:31]
	v_mfma_f32_16x16x32_bf16 v[24:27], v[150:153], v[204:207], v[24:27]
	v_mfma_f32_16x16x32_bf16 v[12:15], v[128:131], v[212:215], v[12:15]
	v_mfma_f32_16x16x32_bf16 v[8:11], v[150:153], v[212:215], v[8:11]
	v_mfma_f32_16x16x32_bf16 v[60:63], v[132:135], v[178:181], v[60:63]
	v_mfma_f32_16x16x32_bf16 v[56:59], v[154:157], v[178:181], v[56:59]
	v_mfma_f32_16x16x32_bf16 v[44:47], v[132:135], v[200:203], v[44:47]
	v_mfma_f32_16x16x32_bf16 v[40:43], v[154:157], v[200:203], v[40:43]
	v_mfma_f32_16x16x32_bf16 v[28:31], v[132:135], v[208:211], v[28:31]
	v_mfma_f32_16x16x32_bf16 v[24:27], v[154:157], v[208:211], v[24:27]
	v_mfma_f32_16x16x32_bf16 v[12:15], v[132:135], v[216:219], v[12:15]
	v_mfma_f32_16x16x32_bf16 v[8:11], v[154:157], v[216:219], v[8:11]
	s_setprio 0
	s_setprio 1
	v_mfma_f32_16x16x32_bf16 v[52:55], v[158:161], v[174:177], v[52:55]
	v_mfma_f32_16x16x32_bf16 v[48:51], v[166:169], v[174:177], v[48:51]
	v_mfma_f32_16x16x32_bf16 v[36:39], v[158:161], v[182:185], v[36:39]
	v_mfma_f32_16x16x32_bf16 v[32:35], v[166:169], v[182:185], v[32:35]
	v_mfma_f32_16x16x32_bf16 v[20:23], v[158:161], v[204:207], v[20:23]
	v_mfma_f32_16x16x32_bf16 v[16:19], v[166:169], v[204:207], v[16:19]
	v_mfma_f32_16x16x32_bf16 v[4:7], v[158:161], v[212:215], v[4:7]
	v_mfma_f32_16x16x32_bf16 v[0:3], v[166:169], v[212:215], v[0:3]
	s_add_i32 s61, s61, 2
	s_add_u32 s6, s6, 0x100
	s_addc_u32 s7, s7, 0
	s_add_u32 s59, s59, 0x100
	s_addc_u32 s60, s60, 0
	s_cmp_gt_u32 s61, 13
	v_mfma_f32_16x16x32_bf16 v[52:55], v[162:165], v[178:181], v[52:55]
	v_mfma_f32_16x16x32_bf16 v[48:51], v[170:173], v[178:181], v[48:51]
	v_mfma_f32_16x16x32_bf16 v[36:39], v[162:165], v[200:203], v[36:39]
	v_mfma_f32_16x16x32_bf16 v[32:35], v[170:173], v[200:203], v[32:35]
	v_mfma_f32_16x16x32_bf16 v[20:23], v[162:165], v[208:211], v[20:23]
	v_mfma_f32_16x16x32_bf16 v[16:19], v[170:173], v[208:211], v[16:19]
	v_mfma_f32_16x16x32_bf16 v[4:7], v[162:165], v[216:219], v[4:7]
	v_mfma_f32_16x16x32_bf16 v[0:3], v[170:173], v[216:219], v[0:3]
	s_setprio 0
	s_barrier
	s_cbranch_scc0 .LBB0_484
	s_and_b64 vcc, exec, s[62:63]
	s_cbranch_vccz .LBB0_487
	s_barrier

; #define PG8_STAGE(bufoff, gbase, voff) do { _Pragma("unroll") for (int _i = 0; _i < 2; ++_i) \
;         __builtin_amdgcn_global_load_lds((const unsigned*)((const char*)(gbase) + (voff)[_i]), (PG8_LAS unsigned*)(lds + (bufoff) + ldsw + _i * 8192), 16, 0, 0); } while (0)
; #define PG8_LDA(dst, b, h) do { _Pragma("unroll") for (int m = 0; m < 4; ++m) _Pragma("unroll") for (int k = 0; k < 2; ++k) dst[m][k] = *(const PG8_LAS bf16x8*)(lds + PG8_SA(b, h) + aoff + m * 2048 + k * 1024); } while (0)
; #define PG8_LDB(dst, b, h) do { _Pragma("unroll") for (int n = 0; n < 2; ++n) _Pragma("unroll") for (int k = 0; k < 2; ++k) dst[n][k] = *(const PG8_LAS bf16x8*)(lds + PG8_SB(b, h) + boff + n * 2048 + k * 1024); } while (0)
; #define PG8_MMA(ai, bj, At, Bt) do { __builtin_amdgcn_s_setprio(1); _Pragma("unroll") for (int m = 0; m < 4; ++m) _Pragma("unroll") for (int n = 0; n < 2; ++n) _Pragma("unroll") for (int k = 0; k < 2; ++k) \
;         acc[ai][bj][m][n] = __builtin_amdgcn_mfma_f32_16x16x32_bf16(Bt[n][k], At[m][k], acc[ai][bj][m][n], 0, 0, 0); __builtin_amdgcn_s_setprio(0); } while (0)
; #define PG8_WAIT_V(n) asm volatile("s_waitcnt vmcnt(" #n ")" ::: "memory")
; #define PG8_WAIT_L(n) asm volatile("s_waitcnt lgkmcnt(" #n ")" ::: "memory")
; template <class Epi, class Sched, bool ALIGN_EPI = false, bool SP2 = false>
; __device__ __forceinline__ void gemm_phase(PG8_LAS unsigned char* lds, const Gemm g, const Sched S, const Epi E) {
;     ...
;             const bool last = (t == nt - 2);
;             const char* a1 = cA + (size_t)(t + 1) * kstep;
;             const char* a2 = last ? nA : cA + (size_t)(t + 2) * kstep; const char* b2 = last ? nB : cB + (size_t)(t + 2) * kstep;
;             const char* a3 = a2 + kstep; const char* b3 = b2 + kstep;
;             if (last && has_next) S.a_ready(nxt);
;             if constexpr (SP2) {
;             PG8_LDB(B0, 0, 0); PG8_LDB(B1, 0, 1); PG8_SCHED; PG8_LDA(At, 0, 0); PG8_STAGE(PG8_SA(1, 1), a1 + hstep, voffA);
;             PG8_WAIT_V(8); PG8_WAIT_L(0); PG8_BAR; PG8_MMA(0, 0, At, B0); PG8_MMA(0, 1, At, B1); PG8_BAR; PG8_SCHED;
;             PG8_LDA(At, 0, 1); PG8_STAGE(PG8_SB(0, 0), b2, voffB); PG8_STAGE(PG8_SB(0, 1), b2 + hstep, voffB); PG8_STAGE(PG8_SA(0, 0), a2, voffA);
;             PG8_WAIT_V(8); PG8_WAIT_L(0); PG8_BAR; PG8_MMA(1, 0, At, B0); PG8_MMA(1, 1, At, B1); PG8_BAR; PG8_SCHED;
.Lpagefit_6:
.LBB0_1025:
	ds_read_b128 v[152:155], v149
	ds_read_b128 v[156:159], v149 offset:1024
	ds_read_b128 v[160:163], v149 offset:2048
	ds_read_b128 v[164:167], v149 offset:3072
	ds_read_b128 v[168:171], v150
	ds_read_b128 v[172:175], v150 offset:1024
	ds_read_b128 v[176:179], v150 offset:2048
	ds_read_b128 v[180:183], v150 offset:3072
	s_add_u32 s42, s40, 0xfffc0080
	s_addc_u32 s43, s41, -1
	s_cmp_eq_u32 s63, 12
	s_cselect_b32 s45, s19, s43
	s_cselect_b32 s44, s59, s42
	s_cselect_b32 s43, s17, s62
	s_cselect_b32 s42, s60, s61
	v_lshl_add_u64 v[144:145], s[40:41], 0, v[136:137]
	s_add_i32 m0, s12, 0xc000
	ds_read_b128 v[190:193], v151
	ds_read_b128 v[194:197], v151 offset:1024
	ds_read_b128 v[198:201], v151 offset:2048
	ds_read_b128 v[202:205], v151 offset:3072
	ds_read_b128 v[206:209], v151 offset:4096
	ds_read_b128 v[210:213], v151 offset:5120
	ds_read_b128 v[214:217], v151 offset:6144
	ds_read_b128 v[218:221], v151 offset:7168
	global_load_lds_dwordx4 v[144:145], off
	v_lshl_add_u64 v[144:145], s[40:41], 0, v[138:139]
	s_add_i32 m0, s12, 0xe000
	s_nop 0
	global_load_lds_dwordx4 v[144:145], off
	s_waitcnt vmcnt(8)
	s_waitcnt lgkmcnt(0)
	s_barrier
	s_setprio 1
	s_waitcnt lgkmcnt(0)
	v_mfma_f32_16x16x32_bf16 v[124:127], v[152:155], v[190:193], v[124:127]
	v_mfma_f32_16x16x32_bf16 v[116:119], v[160:163], v[190:193], v[116:119]
	v_mfma_f32_16x16x32_bf16 v[108:111], v[152:155], v[198:201], v[108:111]
	v_mfma_f32_16x16x32_bf16 v[100:103], v[160:163], v[198:201], v[100:103]
	v_mfma_f32_16x16x32_bf16 v[92:95], v[152:155], v[206:209], v[92:95]
	v_mfma_f32_16x16x32_bf16 v[84:87], v[160:163], v[206:209], v[84:87]
	v_mfma_f32_16x16x32_bf16 v[76:79], v[152:155], v[214:217], v[76:79]
	v_mfma_f32_16x16x32_bf16 v[68:71], v[160:163], v[214:217], v[68:71]
	v_mfma_f32_16x16x32_bf16 v[124:127], v[156:159], v[194:197], v[124:127]
	v_mfma_f32_16x16x32_bf16 v[116:119], v[164:167], v[194:197], v[116:119]
	v_mfma_f32_16x16x32_bf16 v[108:111], v[156:159], v[202:205], v[108:111]
	v_mfma_f32_16x16x32_bf16 v[100:103], v[164:167], v[202:205], v[100:103]
	v_mfma_f32_16x16x32_bf16 v[92:95], v[156:159], v[210:213], v[92:95]
	v_mfma_f32_16x16x32_bf16 v[84:87], v[164:167], v[210:213], v[84:87]
	v_mfma_f32_16x16x32_bf16 v[76:79], v[156:159], v[218:221], v[76:79]
	v_mfma_f32_16x16x32_bf16 v[68:71], v[164:167], v[218:221], v[68:71]
	s_setprio 0
	s_setprio 1
	v_mfma_f32_16x16x32_bf16 v[120:123], v[168:171], v[190:193], v[120:123]
	v_mfma_f32_16x16x32_bf16 v[112:115], v[176:179], v[190:193], v[112:115]
	v_mfma_f32_16x16x32_bf16 v[104:107], v[168:171], v[198:201], v[104:107]
	v_mfma_f32_16x16x32_bf16 v[96:99], v[176:179], v[198:201], v[96:99]
	v_mfma_f32_16x16x32_bf16 v[88:91], v[168:171], v[206:209], v[88:91]
	v_mfma_f32_16x16x32_bf16 v[80:83], v[176:179], v[206:209], v[80:83]
	v_mfma_f32_16x16x32_bf16 v[72:75], v[168:171], v[214:217], v[72:75]
	v_mfma_f32_16x16x32_bf16 v[64:67], v[176:179], v[214:217], v[64:67]
	v_mfma_f32_16x16x32_bf16 v[120:123], v[172:175], v[194:197], v[120:123]
	v_mfma_f32_16x16x32_bf16 v[112:115], v[180:183], v[194:197], v[112:115]
	v_mfma_f32_16x16x32_bf16 v[104:107], v[172:175], v[202:205], v[104:107]
	v_mfma_f32_16x16x32_bf16 v[96:99], v[180:183], v[202:205], v[96:99]
	v_mfma_f32_16x16x32_bf16 v[88:91], v[172:175], v[210:213], v[88:91]
	v_mfma_f32_16x16x32_bf16 v[80:83], v[180:183], v[210:213], v[80:83]
	v_mfma_f32_16x16x32_bf16 v[72:75], v[172:175], v[218:221], v[72:75]
	v_mfma_f32_16x16x32_bf16 v[64:67], v[180:183], v[218:221], v[64:67]
	s_setprio 0
	s_barrier
	s_add_i32 s64, s53, s8
	v_lshl_add_u64 v[144:145], s[42:43], 0, v[132:133]
	s_mov_b32 m0, s64
	ds_read_b128 v[190:193], v151 offset:16384
	ds_read_b128 v[194:197], v151 offset:17408
	ds_read_b128 v[198:201], v151 offset:18432
	ds_read_b128 v[202:205], v151 offset:19456
	ds_read_b128 v[206:209], v151 offset:20480
	ds_read_b128 v[210:213], v151 offset:21504
	ds_read_b128 v[214:217], v151 offset:22528
	ds_read_b128 v[218:221], v151 offset:23552
	global_load_lds_dwordx4 v[144:145], off
	s_add_i32 m0, s64, 0x2000
	s_add_u32 s64, s42, 0x40000
	v_lshl_add_u64 v[184:185], s[42:43], 0, v[128:129]
	s_addc_u32 s65, s43, 0
	s_add_i32 s66, s54, s8
	global_load_lds_dwordx4 v[184:185], off
	v_lshl_add_u64 v[186:187], s[64:65], 0, v[132:133]
	s_mov_b32 m0, s66
	v_lshl_add_u64 v[222:223], s[44:45], 0, v[130:131]
	global_load_lds_dwordx4 v[186:187], off
	v_lshl_add_u64 v[186:187], s[64:65], 0, v[128:129]
	s_add_i32 m0, s66, 0x2000
	s_nop 0
	global_load_lds_dwordx4 v[186:187], off
	v_lshl_add_u64 v[186:187], s[44:45], 0, v[134:135]
	s_mov_b32 m0, s12
	s_nop 0
	global_load_lds_dwordx4 v[186:187], off
	s_mov_b32 m0, s13
	s_nop 0
	global_load_lds_dwordx4 v[222:223], off
	s_waitcnt vmcnt(8)
	s_waitcnt lgkmcnt(0)
	s_barrier
; #define PG8_STAGE(bufoff, gbase, voff) do { _Pragma("unroll") for (int _i = 0; _i < 2; ++_i) \
;         __builtin_amdgcn_global_load_lds((const unsigned*)((const char*)(gbase) + (voff)[_i]), (PG8_LAS unsigned*)(lds + (bufoff) + ldsw + _i * 8192), 16, 0, 0); } while (0)
; #define PG8_LDA(dst, b, h) do { _Pragma("unroll") for (int m = 0; m < 4; ++m) _Pragma("unroll") for (int k = 0; k < 2; ++k) dst[m][k] = *(const PG8_LAS bf16x8*)(lds + PG8_SA(b, h) + aoff + m * 2048 + k * 1024); } while (0)
; #define PG8_LDB(dst, b, h) do { _Pragma("unroll") for (int n = 0; n < 2; ++n) _Pragma("unroll") for (int k = 0; k < 2; ++k) dst[n][k] = *(const PG8_LAS bf16x8*)(lds + PG8_SB(b, h) + boff + n * 2048 + k * 1024); } while (0)
; #define PG8_MMA(ai, bj, At, Bt) do { __builtin_amdgcn_s_setprio(1); _Pragma("unroll") for (int m = 0; m < 4; ++m) _Pragma("unroll") for (int n = 0; n < 2; ++n) _Pragma("unroll") for (int k = 0; k < 2; ++k) \
;         acc[ai][bj][m][n] = __builtin_amdgcn_mfma_f32_16x16x32_bf16(Bt[n][k], At[m][k], acc[ai][bj][m][n], 0, 0, 0); __builtin_amdgcn_s_setprio(0); } while (0)
; #define PG8_WAIT_V(n) asm volatile("s_waitcnt vmcnt(" #n ")" ::: "memory")
; #define PG8_WAIT_L(n) asm volatile("s_waitcnt lgkmcnt(" #n ")" ::: "memory")
; #define PG8_BAR __builtin_amdgcn_s_barrier()
; #define PG8_SCHED __builtin_amdgcn_sched_barrier(0)
; template <class Epi, class Sched, bool ALIGN_EPI = false, bool SP2 = false>
; __device__ __forceinline__ void gemm_phase(PG8_LAS unsigned char* lds, const Gemm g, const Sched S, const Epi E) {
;     ...
;             PG8_WAIT_V(8); PG8_WAIT_L(0); PG8_BAR; PG8_MMA(1, 0, At, B0); PG8_MMA(1, 1, At, B1); PG8_BAR; PG8_SCHED;
;             PG8_LDB(B0, 1, 0); PG8_LDB(B1, 1, 1); PG8_SCHED; PG8_LDA(At, 1, 0); PG8_STAGE(PG8_SA(0, 1), a2 + hstep, voffA);
;             PG8_WAIT_V(8); PG8_WAIT_L(0); PG8_BAR; PG8_MMA(0, 0, At, B0); PG8_MMA(0, 1, At, B1); PG8_BAR; PG8_SCHED;
	s_setprio 1
	s_waitcnt lgkmcnt(0)
	v_mfma_f32_16x16x32_bf16 v[60:63], v[152:155], v[190:193], v[60:63]
	v_mfma_f32_16x16x32_bf16 v[52:55], v[160:163], v[190:193], v[52:55]
	v_mfma_f32_16x16x32_bf16 v[44:47], v[152:155], v[198:201], v[44:47]
	v_mfma_f32_16x16x32_bf16 v[36:39], v[160:163], v[198:201], v[36:39]
	v_mfma_f32_16x16x32_bf16 v[28:31], v[152:155], v[206:209], v[28:31]
	v_mfma_f32_16x16x32_bf16 v[20:23], v[160:163], v[206:209], v[20:23]
	v_mfma_f32_16x16x32_bf16 v[12:15], v[152:155], v[214:217], v[12:15]
	v_mfma_f32_16x16x32_bf16 v[4:7], v[160:163], v[214:217], v[4:7]
	v_mfma_f32_16x16x32_bf16 v[60:63], v[156:159], v[194:197], v[60:63]
	v_mfma_f32_16x16x32_bf16 v[52:55], v[164:167], v[194:197], v[52:55]
	v_mfma_f32_16x16x32_bf16 v[44:47], v[156:159], v[202:205], v[44:47]
	v_mfma_f32_16x16x32_bf16 v[36:39], v[164:167], v[202:205], v[36:39]
	v_mfma_f32_16x16x32_bf16 v[28:31], v[156:159], v[210:213], v[28:31]
	v_mfma_f32_16x16x32_bf16 v[20:23], v[164:167], v[210:213], v[20:23]
	v_mfma_f32_16x16x32_bf16 v[12:15], v[156:159], v[218:221], v[12:15]
	v_mfma_f32_16x16x32_bf16 v[4:7], v[164:167], v[218:221], v[4:7]
	s_setprio 0
	s_setprio 1
	v_mfma_f32_16x16x32_bf16 v[56:59], v[168:171], v[190:193], v[56:59]
	v_mfma_f32_16x16x32_bf16 v[48:51], v[176:179], v[190:193], v[48:51]
	v_mfma_f32_16x16x32_bf16 v[40:43], v[168:171], v[198:201], v[40:43]
	v_mfma_f32_16x16x32_bf16 v[32:35], v[176:179], v[198:201], v[32:35]
	v_mfma_f32_16x16x32_bf16 v[24:27], v[168:171], v[206:209], v[24:27]
	v_mfma_f32_16x16x32_bf16 v[16:19], v[176:179], v[206:209], v[16:19]
	v_mfma_f32_16x16x32_bf16 v[8:11], v[168:171], v[214:217], v[8:11]
	v_mfma_f32_16x16x32_bf16 v[0:3], v[176:179], v[214:217], v[0:3]
	v_mfma_f32_16x16x32_bf16 v[56:59], v[172:175], v[194:197], v[56:59]
	v_mfma_f32_16x16x32_bf16 v[48:51], v[180:183], v[194:197], v[48:51]
	v_mfma_f32_16x16x32_bf16 v[40:43], v[172:175], v[202:205], v[40:43]
	v_mfma_f32_16x16x32_bf16 v[32:35], v[180:183], v[202:205], v[32:35]
	v_mfma_f32_16x16x32_bf16 v[24:27], v[172:175], v[210:213], v[24:27]
	v_mfma_f32_16x16x32_bf16 v[16:19], v[180:183], v[210:213], v[16:19]
	v_mfma_f32_16x16x32_bf16 v[8:11], v[172:175], v[218:221], v[8:11]
	v_mfma_f32_16x16x32_bf16 v[0:3], v[180:183], v[218:221], v[0:3]
	s_setprio 0
	s_barrier
	s_add_i32 s64, 0, 0x18000
	s_add_i32 s65, 0, 0x1c000
	v_add_u32_e32 v164, s64, v148
	v_add_u32_e32 v180, s65, v148
	ds_read_b128 v[152:155], v164
	ds_read_b128 v[156:159], v164 offset:1024
	ds_read_b128 v[160:163], v164 offset:2048
	ds_read_b128 v[164:167], v164 offset:3072
	ds_read_b128 v[168:171], v180
	ds_read_b128 v[172:175], v180 offset:1024
	ds_read_b128 v[176:179], v180 offset:2048
	ds_read_b128 v[180:183], v180 offset:3072
	s_add_u32 s44, s44, 0x40000
	s_addc_u32 s45, s45, 0
	s_mov_b32 m0, s33
	v_lshl_add_u64 v[224:225], s[44:45], 0, v[134:135]
	ds_read_b128 v[190:193], v151 offset:32768
	ds_read_b128 v[194:197], v151 offset:33792
	ds_read_b128 v[198:201], v151 offset:34816
	ds_read_b128 v[202:205], v151 offset:35840
	ds_read_b128 v[206:209], v151 offset:36864
	ds_read_b128 v[210:213], v151 offset:37888
	ds_read_b128 v[214:217], v151 offset:38912
	ds_read_b128 v[218:221], v151 offset:39936
	global_load_lds_dwordx4 v[224:225], off
	v_lshl_add_u64 v[224:225], s[44:45], 0, v[130:131]
	s_mov_b32 m0, s39
	s_nop 0
	global_load_lds_dwordx4 v[224:225], off
	s_waitcnt vmcnt(8)
	s_waitcnt lgkmcnt(0)
	s_barrier
	s_setprio 1
	s_waitcnt lgkmcnt(0)
	v_mfma_f32_16x16x32_bf16 v[124:127], v[152:155], v[190:193], v[124:127]
	v_mfma_f32_16x16x32_bf16 v[116:119], v[160:163], v[190:193], v[116:119]
	v_mfma_f32_16x16x32_bf16 v[108:111], v[152:155], v[198:201], v[108:111]
	v_mfma_f32_16x16x32_bf16 v[100:103], v[160:163], v[198:201], v[100:103]
	v_mfma_f32_16x16x32_bf16 v[92:95], v[152:155], v[206:209], v[92:95]
	v_mfma_f32_16x16x32_bf16 v[84:87], v[160:163], v[206:209], v[84:87]
	v_mfma_f32_16x16x32_bf16 v[76:79], v[152:155], v[214:217], v[76:79]
	v_mfma_f32_16x16x32_bf16 v[68:71], v[160:163], v[214:217], v[68:71]
	v_mfma_f32_16x16x32_bf16 v[124:127], v[156:159], v[194:197], v[124:127]
	v_mfma_f32_16x16x32_bf16 v[116:119], v[164:167], v[194:197], v[116:119]
	v_mfma_f32_16x16x32_bf16 v[108:111], v[156:159], v[202:205], v[108:111]
	v_mfma_f32_16x16x32_bf16 v[100:103], v[164:167], v[202:205], v[100:103]
	v_mfma_f32_16x16x32_bf16 v[92:95], v[156:159], v[210:213], v[92:95]
	v_mfma_f32_16x16x32_bf16 v[84:87], v[164:167], v[210:213], v[84:87]
	v_mfma_f32_16x16x32_bf16 v[76:79], v[156:159], v[218:221], v[76:79]
	v_mfma_f32_16x16x32_bf16 v[68:71], v[164:167], v[218:221], v[68:71]
	s_setprio 0
	s_setprio 1
	v_mfma_f32_16x16x32_bf16 v[120:123], v[168:171], v[190:193], v[120:123]
	v_mfma_f32_16x16x32_bf16 v[112:115], v[176:179], v[190:193], v[112:115]
	v_mfma_f32_16x16x32_bf16 v[104:107], v[168:171], v[198:201], v[104:107]
	v_mfma_f32_16x16x32_bf16 v[96:99], v[176:179], v[198:201], v[96:99]
	v_mfma_f32_16x16x32_bf16 v[88:91], v[168:171], v[206:209], v[88:91]
	v_mfma_f32_16x16x32_bf16 v[80:83], v[176:179], v[206:209], v[80:83]
	v_mfma_f32_16x16x32_bf16 v[72:75], v[168:171], v[214:217], v[72:75]
	v_mfma_f32_16x16x32_bf16 v[64:67], v[176:179], v[214:217], v[64:67]
	v_mfma_f32_16x16x32_bf16 v[120:123], v[172:175], v[194:197], v[120:123]
	v_mfma_f32_16x16x32_bf16 v[112:115], v[180:183], v[194:197], v[112:115]
	v_mfma_f32_16x16x32_bf16 v[104:107], v[172:175], v[202:205], v[104:107]
	v_mfma_f32_16x16x32_bf16 v[96:99], v[180:183], v[202:205], v[96:99]
	v_mfma_f32_16x16x32_bf16 v[88:91], v[172:175], v[210:213], v[88:91]
	v_mfma_f32_16x16x32_bf16 v[80:83], v[180:183], v[210:213], v[80:83]
	v_mfma_f32_16x16x32_bf16 v[72:75], v[172:175], v[218:221], v[72:75]
	v_mfma_f32_16x16x32_bf16 v[64:67], v[180:183], v[218:221], v[64:67]
	s_setprio 0
	s_barrier
; #define PG8_STAGE(bufoff, gbase, voff) do { _Pragma("unroll") for (int _i = 0; _i < 2; ++_i) \
;         __builtin_amdgcn_global_load_lds((const unsigned*)((const char*)(gbase) + (voff)[_i]), (PG8_LAS unsigned*)(lds + (bufoff) + ldsw + _i * 8192), 16, 0, 0); } while (0)
; #define PG8_LDA(dst, b, h) do { _Pragma("unroll") for (int m = 0; m < 4; ++m) _Pragma("unroll") for (int k = 0; k < 2; ++k) dst[m][k] = *(const PG8_LAS bf16x8*)(lds + PG8_SA(b, h) + aoff + m * 2048 + k * 1024); } while (0)
; #define PG8_MMA(ai, bj, At, Bt) do { __builtin_amdgcn_s_setprio(1); _Pragma("unroll") for (int m = 0; m < 4; ++m) _Pragma("unroll") for (int n = 0; n < 2; ++n) _Pragma("unroll") for (int k = 0; k < 2; ++k) \
;         acc[ai][bj][m][n] = __builtin_amdgcn_mfma_f32_16x16x32_bf16(Bt[n][k], At[m][k], acc[ai][bj][m][n], 0, 0, 0); __builtin_amdgcn_s_setprio(0); } while (0)
; #define PG8_WAIT_V(n) asm volatile("s_waitcnt vmcnt(" #n ")" ::: "memory")
; #define PG8_WAIT_L(n) asm volatile("s_waitcnt lgkmcnt(" #n ")" ::: "memory")
; #define PG8_BAR __builtin_amdgcn_s_barrier()
; #define PG8_SCHED __builtin_amdgcn_sched_barrier(0)
; template <class Epi, class Sched, bool ALIGN_EPI = false, bool SP2 = false>
; __device__ __forceinline__ void gemm_phase(PG8_LAS unsigned char* lds, const Gemm g, const Sched S, const Epi E) {
;     ...
;         for (int t = 0; t < nt; t += 2) {
;             if constexpr (Epi::MIDT >= 0) { if (t == Epi::MIDT) E.mid(acc, cur, wr, fr); }
;             const bool last = (t == nt - 2);
;             const char* a1 = cA + (size_t)(t + 1) * kstep;
;             const char* a2 = last ? nA : cA + (size_t)(t + 2) * kstep; const char* b2 = last ? nB : cB + (size_t)(t + 2) * kstep;
;     ...
;             PG8_LDA(At, 1, 1); PG8_STAGE(PG8_SB(1, 0), b3, voffB); PG8_STAGE(PG8_SB(1, 1), b3 + hstep, voffB); PG8_STAGE(PG8_SA(1, 0), a3, voffA);
;             PG8_WAIT_V(8); PG8_WAIT_L(0); PG8_BAR; PG8_MMA(1, 0, At, B0); PG8_MMA(1, 1, At, B1); PG8_BAR; PG8_SCHED;
	s_add_i32 s44, s64, s8
	v_lshl_add_u64 v[144:145], v[144:145], 0, s[10:11]
	s_mov_b32 m0, s44
	ds_read_b128 v[190:193], v151 offset:49152
	ds_read_b128 v[194:197], v151 offset:50176
	ds_read_b128 v[198:201], v151 offset:51200
	ds_read_b128 v[202:205], v151 offset:52224
	ds_read_b128 v[206:209], v151 offset:53248
	ds_read_b128 v[210:213], v151 offset:54272
	ds_read_b128 v[214:217], v151 offset:55296
	ds_read_b128 v[218:221], v151 offset:56320
	global_load_lds_dwordx4 v[144:145], off
	s_add_i32 m0, s44, 0x2000
	s_add_u32 s42, s42, 0x40080
	v_lshl_add_u64 v[144:145], v[184:185], 0, s[10:11]
	s_addc_u32 s43, s43, 0
	s_add_i32 s44, s65, s8
	global_load_lds_dwordx4 v[144:145], off
	v_lshl_add_u64 v[144:145], s[42:43], 0, v[132:133]
	s_mov_b32 m0, s44
	s_nop 0
	global_load_lds_dwordx4 v[144:145], off
	v_lshl_add_u64 v[144:145], s[42:43], 0, v[128:129]
	s_add_i32 m0, s44, 0x2000
	s_nop 0
	global_load_lds_dwordx4 v[144:145], off
	v_lshl_add_u64 v[144:145], v[186:187], 0, s[10:11]
	s_mov_b32 m0, s49
	s_nop 0
	global_load_lds_dwordx4 v[144:145], off
	v_lshl_add_u64 v[144:145], v[222:223], 0, s[10:11]
	s_mov_b32 m0, s50
	s_nop 0
	global_load_lds_dwordx4 v[144:145], off
	s_waitcnt vmcnt(8)
	s_waitcnt lgkmcnt(0)
	s_barrier
	s_setprio 1
	s_waitcnt lgkmcnt(0)
	v_mfma_f32_16x16x32_bf16 v[60:63], v[152:155], v[190:193], v[60:63]
	v_mfma_f32_16x16x32_bf16 v[52:55], v[160:163], v[190:193], v[52:55]
	v_mfma_f32_16x16x32_bf16 v[44:47], v[152:155], v[198:201], v[44:47]
	v_mfma_f32_16x16x32_bf16 v[36:39], v[160:163], v[198:201], v[36:39]
	v_mfma_f32_16x16x32_bf16 v[28:31], v[152:155], v[206:209], v[28:31]
	v_mfma_f32_16x16x32_bf16 v[20:23], v[160:163], v[206:209], v[20:23]
	v_mfma_f32_16x16x32_bf16 v[12:15], v[152:155], v[214:217], v[12:15]
	v_mfma_f32_16x16x32_bf16 v[4:7], v[160:163], v[214:217], v[4:7]
	v_mfma_f32_16x16x32_bf16 v[60:63], v[156:159], v[194:197], v[60:63]
	v_mfma_f32_16x16x32_bf16 v[52:55], v[164:167], v[194:197], v[52:55]
	v_mfma_f32_16x16x32_bf16 v[44:47], v[156:159], v[202:205], v[44:47]
	v_mfma_f32_16x16x32_bf16 v[36:39], v[164:167], v[202:205], v[36:39]
	v_mfma_f32_16x16x32_bf16 v[28:31], v[156:159], v[210:213], v[28:31]
	v_mfma_f32_16x16x32_bf16 v[20:23], v[164:167], v[210:213], v[20:23]
	v_mfma_f32_16x16x32_bf16 v[12:15], v[156:159], v[218:221], v[12:15]
	v_mfma_f32_16x16x32_bf16 v[4:7], v[164:167], v[218:221], v[4:7]
	s_setprio 0
	s_setprio 1
	v_mfma_f32_16x16x32_bf16 v[56:59], v[168:171], v[190:193], v[56:59]
	v_mfma_f32_16x16x32_bf16 v[48:51], v[176:179], v[190:193], v[48:51]
	v_mfma_f32_16x16x32_bf16 v[40:43], v[168:171], v[198:201], v[40:43]
	v_mfma_f32_16x16x32_bf16 v[32:35], v[176:179], v[198:201], v[32:35]
	v_mfma_f32_16x16x32_bf16 v[24:27], v[168:171], v[206:209], v[24:27]
	v_mfma_f32_16x16x32_bf16 v[16:19], v[176:179], v[206:209], v[16:19]
	v_mfma_f32_16x16x32_bf16 v[8:11], v[168:171], v[214:217], v[8:11]
	v_mfma_f32_16x16x32_bf16 v[0:3], v[176:179], v[214:217], v[0:3]
	s_add_i32 s63, s63, 2
	s_add_u32 s40, s40, 0x100
	s_addc_u32 s41, s41, 0
	s_add_u32 s61, s61, 0x100
	s_addc_u32 s62, s62, 0
	s_cmp_gt_u32 s63, 13
	v_mfma_f32_16x16x32_bf16 v[56:59], v[172:175], v[194:197], v[56:59]
	v_mfma_f32_16x16x32_bf16 v[48:51], v[180:183], v[194:197], v[48:51]
	v_mfma_f32_16x16x32_bf16 v[40:43], v[172:175], v[202:205], v[40:43]
	v_mfma_f32_16x16x32_bf16 v[32:35], v[180:183], v[202:205], v[32:35]
	v_mfma_f32_16x16x32_bf16 v[24:27], v[172:175], v[210:213], v[24:27]
	v_mfma_f32_16x16x32_bf16 v[16:19], v[180:183], v[210:213], v[16:19]
	v_mfma_f32_16x16x32_bf16 v[8:11], v[172:175], v[218:221], v[8:11]
	v_mfma_f32_16x16x32_bf16 v[0:3], v[180:183], v[218:221], v[0:3]
	s_setprio 0
	s_barrier
	s_cbranch_scc0 .LBB0_1025
	s_and_b64 vcc, exec, s[14:15]
	s_cbranch_vccz .LBB0_1028
	s_barrier

; #define PG8_STAGE(bufoff, gbase, voff) do { _Pragma("unroll") for (int _i = 0; _i < 2; ++_i) \
;         __builtin_amdgcn_global_load_lds((const unsigned*)((const char*)(gbase) + (voff)[_i]), (PG8_LAS unsigned*)(lds + (bufoff) + ldsw + _i * 8192), 16, 0, 0); } while (0)
; #define PG8_LDA(dst, b, h) do { _Pragma("unroll") for (int m = 0; m < 4; ++m) _Pragma("unroll") for (int k = 0; k < 2; ++k) dst[m][k] = *(const PG8_LAS bf16x8*)(lds + PG8_SA(b, h) + aoff + m * 2048 + k * 1024); } while (0)
; #define PG8_LDB(dst, b, h) do { _Pragma("unroll") for (int n = 0; n < 2; ++n) _Pragma("unroll") for (int k = 0; k < 2; ++k) dst[n][k] = *(const PG8_LAS bf16x8*)(lds + PG8_SB(b, h) + boff + n * 2048 + k * 1024); } while (0)
; #define PG8_MMA(ai, bj, At, Bt) do { __builtin_amdgcn_s_setprio(1); _Pragma("unroll") for (int m = 0; m < 4; ++m) _Pragma("unroll") for (int n = 0; n < 2; ++n) _Pragma("unroll") for (int k = 0; k < 2; ++k) \
;         acc[ai][bj][m][n] = __builtin_amdgcn_mfma_f32_16x16x32_bf16(Bt[n][k], At[m][k], acc[ai][bj][m][n], 0, 0, 0); __builtin_amdgcn_s_setprio(0); } while (0)
; #define PG8_WAIT_V(n) asm volatile("s_waitcnt vmcnt(" #n ")" ::: "memory")
; #define PG8_WAIT_L(n) asm volatile("s_waitcnt lgkmcnt(" #n ")" ::: "memory")
; template <class Epi, class Sched, bool ALIGN_EPI = false, bool SP2 = false>
; __device__ __forceinline__ void gemm_phase(PG8_LAS unsigned char* lds, const Gemm g, const Sched S, const Epi E) {
;     ...
;             const bool last = (t == nt - 2);
;             const char* a1 = cA + (size_t)(t + 1) * kstep;
;             const char* a2 = last ? nA : cA + (size_t)(t + 2) * kstep; const char* b2 = last ? nB : cB + (size_t)(t + 2) * kstep;
;             const char* a3 = a2 + kstep; const char* b3 = b2 + kstep;
;             if (last && has_next) S.a_ready(nxt);
;             if constexpr (SP2) {
;             PG8_LDB(B0, 0, 0); PG8_LDB(B1, 0, 1); PG8_SCHED; PG8_LDA(At, 0, 0); PG8_STAGE(PG8_SA(1, 1), a1 + hstep, voffA);
;             PG8_WAIT_V(8); PG8_WAIT_L(0); PG8_BAR; PG8_MMA(0, 0, At, B0); PG8_MMA(0, 1, At, B1); PG8_BAR; PG8_SCHED;
;             PG8_LDA(At, 0, 1); PG8_STAGE(PG8_SB(0, 0), b2, voffB); PG8_STAGE(PG8_SB(0, 1), b2 + hstep, voffB); PG8_STAGE(PG8_SA(0, 0), a2, voffA);
;             PG8_WAIT_V(8); PG8_WAIT_L(0); PG8_BAR; PG8_MMA(1, 0, At, B0); PG8_MMA(1, 1, At, B1); PG8_BAR; PG8_SCHED;
.LBB0_1105:
	ds_read_b128 v[128:131], v241
	ds_read_b128 v[132:135], v241 offset:1024
	ds_read_b128 v[136:139], v241 offset:2048
	ds_read_b128 v[140:143], v241 offset:3072
	ds_read_b128 v[144:147], v242
	ds_read_b128 v[148:151], v242 offset:1024
	ds_read_b128 v[152:155], v242 offset:2048
	ds_read_b128 v[156:159], v242 offset:3072
	s_add_u32 s48, s46, 0x100
	s_addc_u32 s49, s47, 0
	s_cmp_eq_u32 s71, 40
	s_cselect_b32 s53, s5, s49
	s_cselect_b32 s52, s4, s48
	s_cselect_b32 s51, s45, s70
	s_cselect_b32 s50, s44, s69
	v_lshl_add_u64 v[210:211], s[46:47], 0, v[198:199]
	s_add_i32 m0, s9, 0xc000
	ds_read_b128 v[160:163], v243
	ds_read_b128 v[164:167], v243 offset:1024
	ds_read_b128 v[168:171], v243 offset:2048
	ds_read_b128 v[172:175], v243 offset:3072
	ds_read_b128 v[176:179], v243 offset:4096
	ds_read_b128 v[180:183], v243 offset:5120
	ds_read_b128 v[184:187], v243 offset:6144
	ds_read_b128 v[206:209], v243 offset:7168
	global_load_lds_dwordx4 v[210:211], off
	v_lshl_add_u64 v[210:211], s[46:47], 0, v[200:201]
	s_add_i32 m0, s9, 0xe000
	s_nop 0
	global_load_lds_dwordx4 v[210:211], off
	s_waitcnt vmcnt(8)
	s_waitcnt lgkmcnt(0)
	s_barrier
	s_setprio 1
	s_waitcnt lgkmcnt(0)
	v_mfma_f32_16x16x32_bf16 v[124:127], v[128:131], v[160:163], v[124:127]
	v_mfma_f32_16x16x32_bf16 v[120:123], v[136:139], v[160:163], v[120:123]
	v_mfma_f32_16x16x32_bf16 v[112:115], v[128:131], v[168:171], v[112:115]
	v_mfma_f32_16x16x32_bf16 v[104:107], v[136:139], v[168:171], v[104:107]
	v_mfma_f32_16x16x32_bf16 v[96:99], v[128:131], v[176:179], v[96:99]
	v_mfma_f32_16x16x32_bf16 v[88:91], v[136:139], v[176:179], v[88:91]
	v_mfma_f32_16x16x32_bf16 v[80:83], v[128:131], v[184:187], v[80:83]
	v_mfma_f32_16x16x32_bf16 v[72:75], v[136:139], v[184:187], v[72:75]
	v_mfma_f32_16x16x32_bf16 v[124:127], v[132:135], v[164:167], v[124:127]
	v_mfma_f32_16x16x32_bf16 v[120:123], v[140:143], v[164:167], v[120:123]
	v_mfma_f32_16x16x32_bf16 v[112:115], v[132:135], v[172:175], v[112:115]
	v_mfma_f32_16x16x32_bf16 v[104:107], v[140:143], v[172:175], v[104:107]
	v_mfma_f32_16x16x32_bf16 v[96:99], v[132:135], v[180:183], v[96:99]
	v_mfma_f32_16x16x32_bf16 v[88:91], v[140:143], v[180:183], v[88:91]
	v_mfma_f32_16x16x32_bf16 v[80:83], v[132:135], v[206:209], v[80:83]
	v_mfma_f32_16x16x32_bf16 v[72:75], v[140:143], v[206:209], v[72:75]
	s_setprio 0
	s_setprio 1
	v_mfma_f32_16x16x32_bf16 v[116:119], v[144:147], v[160:163], v[116:119]
	v_mfma_f32_16x16x32_bf16 v[108:111], v[152:155], v[160:163], v[108:111]
	v_mfma_f32_16x16x32_bf16 v[100:103], v[144:147], v[168:171], v[100:103]
	v_mfma_f32_16x16x32_bf16 v[92:95], v[152:155], v[168:171], v[92:95]
	v_mfma_f32_16x16x32_bf16 v[84:87], v[144:147], v[176:179], v[84:87]
	v_mfma_f32_16x16x32_bf16 v[76:79], v[152:155], v[176:179], v[76:79]
	v_mfma_f32_16x16x32_bf16 v[68:71], v[144:147], v[184:187], v[68:71]
	v_mfma_f32_16x16x32_bf16 v[64:67], v[152:155], v[184:187], v[64:67]
	v_mfma_f32_16x16x32_bf16 v[116:119], v[148:151], v[164:167], v[116:119]
	v_mfma_f32_16x16x32_bf16 v[108:111], v[156:159], v[164:167], v[108:111]
	v_mfma_f32_16x16x32_bf16 v[100:103], v[148:151], v[172:175], v[100:103]
	v_mfma_f32_16x16x32_bf16 v[92:95], v[156:159], v[172:175], v[92:95]
	v_mfma_f32_16x16x32_bf16 v[84:87], v[148:151], v[180:183], v[84:87]
	v_mfma_f32_16x16x32_bf16 v[76:79], v[156:159], v[180:183], v[76:79]
	v_mfma_f32_16x16x32_bf16 v[68:71], v[148:151], v[206:209], v[68:71]
	v_mfma_f32_16x16x32_bf16 v[64:67], v[156:159], v[206:209], v[64:67]
	s_setprio 0
	s_barrier
	s_add_i32 s46, s63, s8
	v_lshl_add_u64 v[210:211], s[50:51], 0, v[192:193]
	s_mov_b32 m0, s46
	ds_read_b128 v[160:163], v243 offset:16384
	ds_read_b128 v[164:167], v243 offset:17408
	ds_read_b128 v[168:171], v243 offset:18432
	ds_read_b128 v[172:175], v243 offset:19456
	ds_read_b128 v[176:179], v243 offset:20480
	ds_read_b128 v[180:183], v243 offset:21504
	ds_read_b128 v[184:187], v243 offset:22528
	ds_read_b128 v[206:209], v243 offset:23552
	global_load_lds_dwordx4 v[210:211], off
	s_add_i32 m0, s46, 0x2000
	s_add_u32 s46, s50, 0xb0000
	v_lshl_add_u64 v[212:213], s[50:51], 0, v[196:197]
	s_addc_u32 s47, s51, 0
	s_add_i32 s72, s64, s8
	global_load_lds_dwordx4 v[212:213], off
	v_lshl_add_u64 v[214:215], s[46:47], 0, v[192:193]
	s_mov_b32 m0, s72
	v_lshl_add_u64 v[216:217], s[52:53], 0, v[194:195]
	global_load_lds_dwordx4 v[214:215], off
	v_lshl_add_u64 v[214:215], s[46:47], 0, v[196:197]
	s_add_i32 m0, s72, 0x2000
	s_nop 0
	global_load_lds_dwordx4 v[214:215], off
	v_lshl_add_u64 v[214:215], s[52:53], 0, v[190:191]
	s_mov_b32 m0, s9
	s_nop 0
	global_load_lds_dwordx4 v[214:215], off
	s_mov_b32 m0, s12
	s_nop 0
	global_load_lds_dwordx4 v[216:217], off
	s_waitcnt vmcnt(8)
	s_waitcnt lgkmcnt(0)
	s_barrier
; #define PG8_STAGE(bufoff, gbase, voff) do { _Pragma("unroll") for (int _i = 0; _i < 2; ++_i) \
;         __builtin_amdgcn_global_load_lds((const unsigned*)((const char*)(gbase) + (voff)[_i]), (PG8_LAS unsigned*)(lds + (bufoff) + ldsw + _i * 8192), 16, 0, 0); } while (0)
; #define PG8_LDA(dst, b, h) do { _Pragma("unroll") for (int m = 0; m < 4; ++m) _Pragma("unroll") for (int k = 0; k < 2; ++k) dst[m][k] = *(const PG8_LAS bf16x8*)(lds + PG8_SA(b, h) + aoff + m * 2048 + k * 1024); } while (0)
; #define PG8_LDB(dst, b, h) do { _Pragma("unroll") for (int n = 0; n < 2; ++n) _Pragma("unroll") for (int k = 0; k < 2; ++k) dst[n][k] = *(const PG8_LAS bf16x8*)(lds + PG8_SB(b, h) + boff + n * 2048 + k * 1024); } while (0)
; #define PG8_MMA(ai, bj, At, Bt) do { __builtin_amdgcn_s_setprio(1); _Pragma("unroll") for (int m = 0; m < 4; ++m) _Pragma("unroll") for (int n = 0; n < 2; ++n) _Pragma("unroll") for (int k = 0; k < 2; ++k) \
;         acc[ai][bj][m][n] = __builtin_amdgcn_mfma_f32_16x16x32_bf16(Bt[n][k], At[m][k], acc[ai][bj][m][n], 0, 0, 0); __builtin_amdgcn_s_setprio(0); } while (0)
; #define PG8_WAIT_V(n) asm volatile("s_waitcnt vmcnt(" #n ")" ::: "memory")
; #define PG8_WAIT_L(n) asm volatile("s_waitcnt lgkmcnt(" #n ")" ::: "memory")
; #define PG8_BAR __builtin_amdgcn_s_barrier()
; #define PG8_SCHED __builtin_amdgcn_sched_barrier(0)
; template <class Epi, class Sched, bool ALIGN_EPI = false, bool SP2 = false>
; __device__ __forceinline__ void gemm_phase(PG8_LAS unsigned char* lds, const Gemm g, const Sched S, const Epi E) {
;     ...
;             PG8_WAIT_V(8); PG8_WAIT_L(0); PG8_BAR; PG8_MMA(1, 0, At, B0); PG8_MMA(1, 1, At, B1); PG8_BAR; PG8_SCHED;
;             PG8_LDB(B0, 1, 0); PG8_LDB(B1, 1, 1); PG8_SCHED; PG8_LDA(At, 1, 0); PG8_STAGE(PG8_SA(0, 1), a2 + hstep, voffA);
;             PG8_WAIT_V(8); PG8_WAIT_L(0); PG8_BAR; PG8_MMA(0, 0, At, B0); PG8_MMA(0, 1, At, B1); PG8_BAR; PG8_SCHED;
	s_setprio 1
	s_waitcnt lgkmcnt(0)
	v_mfma_f32_16x16x32_bf16 v[60:63], v[128:131], v[160:163], v[60:63]
	v_mfma_f32_16x16x32_bf16 v[56:59], v[136:139], v[160:163], v[56:59]
	v_mfma_f32_16x16x32_bf16 v[48:51], v[128:131], v[168:171], v[48:51]
	v_mfma_f32_16x16x32_bf16 v[40:43], v[136:139], v[168:171], v[40:43]
	v_mfma_f32_16x16x32_bf16 v[32:35], v[128:131], v[176:179], v[32:35]
	v_mfma_f32_16x16x32_bf16 v[24:27], v[136:139], v[176:179], v[24:27]
	v_mfma_f32_16x16x32_bf16 v[16:19], v[128:131], v[184:187], v[16:19]
	v_mfma_f32_16x16x32_bf16 v[8:11], v[136:139], v[184:187], v[8:11]
	v_mfma_f32_16x16x32_bf16 v[60:63], v[132:135], v[164:167], v[60:63]
	v_mfma_f32_16x16x32_bf16 v[56:59], v[140:143], v[164:167], v[56:59]
	v_mfma_f32_16x16x32_bf16 v[48:51], v[132:135], v[172:175], v[48:51]
	v_mfma_f32_16x16x32_bf16 v[40:43], v[140:143], v[172:175], v[40:43]
	v_mfma_f32_16x16x32_bf16 v[32:35], v[132:135], v[180:183], v[32:35]
	v_mfma_f32_16x16x32_bf16 v[24:27], v[140:143], v[180:183], v[24:27]
	v_mfma_f32_16x16x32_bf16 v[16:19], v[132:135], v[206:209], v[16:19]
	v_mfma_f32_16x16x32_bf16 v[8:11], v[140:143], v[206:209], v[8:11]
	s_setprio 0
	s_setprio 1
	v_mfma_f32_16x16x32_bf16 v[52:55], v[144:147], v[160:163], v[52:55]
	v_mfma_f32_16x16x32_bf16 v[44:47], v[152:155], v[160:163], v[44:47]
	v_mfma_f32_16x16x32_bf16 v[36:39], v[144:147], v[168:171], v[36:39]
	v_mfma_f32_16x16x32_bf16 v[28:31], v[152:155], v[168:171], v[28:31]
	v_mfma_f32_16x16x32_bf16 v[20:23], v[144:147], v[176:179], v[20:23]
	v_mfma_f32_16x16x32_bf16 v[12:15], v[152:155], v[176:179], v[12:15]
	v_mfma_f32_16x16x32_bf16 v[4:7], v[144:147], v[184:187], v[4:7]
	v_mfma_f32_16x16x32_bf16 v[0:3], v[152:155], v[184:187], v[0:3]
	v_mfma_f32_16x16x32_bf16 v[52:55], v[148:151], v[164:167], v[52:55]
	v_mfma_f32_16x16x32_bf16 v[44:47], v[156:159], v[164:167], v[44:47]
	v_mfma_f32_16x16x32_bf16 v[36:39], v[148:151], v[172:175], v[36:39]
	v_mfma_f32_16x16x32_bf16 v[28:31], v[156:159], v[172:175], v[28:31]
	v_mfma_f32_16x16x32_bf16 v[20:23], v[148:151], v[180:183], v[20:23]
	v_mfma_f32_16x16x32_bf16 v[12:15], v[156:159], v[180:183], v[12:15]
	v_mfma_f32_16x16x32_bf16 v[4:7], v[148:151], v[206:209], v[4:7]
	v_mfma_f32_16x16x32_bf16 v[0:3], v[156:159], v[206:209], v[0:3]
	s_setprio 0
	s_barrier
	s_add_i32 s72, 0, 0x18000
	s_add_i32 s73, 0, 0x1c000
	v_add_u32_e32 v140, s72, v240
	v_add_u32_e32 v156, s73, v240
	ds_read_b128 v[128:131], v140
	ds_read_b128 v[132:135], v140 offset:1024
	ds_read_b128 v[136:139], v140 offset:2048
	ds_read_b128 v[140:143], v140 offset:3072
	ds_read_b128 v[144:147], v156
	ds_read_b128 v[148:151], v156 offset:1024
	ds_read_b128 v[152:155], v156 offset:2048
	ds_read_b128 v[156:159], v156 offset:3072
	s_add_u32 s46, s52, 0xb0000
	s_addc_u32 s47, s53, 0
	s_mov_b32 m0, s13
	v_lshl_add_u64 v[218:219], s[46:47], 0, v[190:191]
	ds_read_b128 v[160:163], v243 offset:32768
	ds_read_b128 v[164:167], v243 offset:33792
	ds_read_b128 v[168:171], v243 offset:34816
	ds_read_b128 v[172:175], v243 offset:35840
	ds_read_b128 v[176:179], v243 offset:36864
	ds_read_b128 v[180:183], v243 offset:37888
	ds_read_b128 v[184:187], v243 offset:38912
	ds_read_b128 v[206:209], v243 offset:39936
	global_load_lds_dwordx4 v[218:219], off
	v_lshl_add_u64 v[218:219], s[46:47], 0, v[194:195]
	s_mov_b32 m0, s33
	s_nop 0
	global_load_lds_dwordx4 v[218:219], off
	s_waitcnt vmcnt(8)
	s_waitcnt lgkmcnt(0)
	s_barrier
	s_setprio 1
	s_waitcnt lgkmcnt(0)
	v_mfma_f32_16x16x32_bf16 v[124:127], v[128:131], v[160:163], v[124:127]
	v_mfma_f32_16x16x32_bf16 v[120:123], v[136:139], v[160:163], v[120:123]
	v_mfma_f32_16x16x32_bf16 v[112:115], v[128:131], v[168:171], v[112:115]
	v_mfma_f32_16x16x32_bf16 v[104:107], v[136:139], v[168:171], v[104:107]
	v_mfma_f32_16x16x32_bf16 v[96:99], v[128:131], v[176:179], v[96:99]
	v_mfma_f32_16x16x32_bf16 v[88:91], v[136:139], v[176:179], v[88:91]
	v_mfma_f32_16x16x32_bf16 v[80:83], v[128:131], v[184:187], v[80:83]
	v_mfma_f32_16x16x32_bf16 v[72:75], v[136:139], v[184:187], v[72:75]
	v_mfma_f32_16x16x32_bf16 v[124:127], v[132:135], v[164:167], v[124:127]
	v_mfma_f32_16x16x32_bf16 v[120:123], v[140:143], v[164:167], v[120:123]
	v_mfma_f32_16x16x32_bf16 v[112:115], v[132:135], v[172:175], v[112:115]
	v_mfma_f32_16x16x32_bf16 v[104:107], v[140:143], v[172:175], v[104:107]
	v_mfma_f32_16x16x32_bf16 v[96:99], v[132:135], v[180:183], v[96:99]
	v_mfma_f32_16x16x32_bf16 v[88:91], v[140:143], v[180:183], v[88:91]
	v_mfma_f32_16x16x32_bf16 v[80:83], v[132:135], v[206:209], v[80:83]
	v_mfma_f32_16x16x32_bf16 v[72:75], v[140:143], v[206:209], v[72:75]
	s_setprio 0
	s_setprio 1
	v_mfma_f32_16x16x32_bf16 v[116:119], v[144:147], v[160:163], v[116:119]
	v_mfma_f32_16x16x32_bf16 v[108:111], v[152:155], v[160:163], v[108:111]
	v_mfma_f32_16x16x32_bf16 v[100:103], v[144:147], v[168:171], v[100:103]
	v_mfma_f32_16x16x32_bf16 v[92:95], v[152:155], v[168:171], v[92:95]
	v_mfma_f32_16x16x32_bf16 v[84:87], v[144:147], v[176:179], v[84:87]
	v_mfma_f32_16x16x32_bf16 v[76:79], v[152:155], v[176:179], v[76:79]
	v_mfma_f32_16x16x32_bf16 v[68:71], v[144:147], v[184:187], v[68:71]
	v_mfma_f32_16x16x32_bf16 v[64:67], v[152:155], v[184:187], v[64:67]
	v_mfma_f32_16x16x32_bf16 v[116:119], v[148:151], v[164:167], v[116:119]
	v_mfma_f32_16x16x32_bf16 v[108:111], v[156:159], v[164:167], v[108:111]
	v_mfma_f32_16x16x32_bf16 v[100:103], v[148:151], v[172:175], v[100:103]
	v_mfma_f32_16x16x32_bf16 v[92:95], v[156:159], v[172:175], v[92:95]
	v_mfma_f32_16x16x32_bf16 v[84:87], v[148:151], v[180:183], v[84:87]
	v_mfma_f32_16x16x32_bf16 v[76:79], v[156:159], v[180:183], v[76:79]
	v_mfma_f32_16x16x32_bf16 v[68:71], v[148:151], v[206:209], v[68:71]
	v_mfma_f32_16x16x32_bf16 v[64:67], v[156:159], v[206:209], v[64:67]
	s_setprio 0
	s_barrier
; #define PG8_STAGE(bufoff, gbase, voff) do { _Pragma("unroll") for (int _i = 0; _i < 2; ++_i) \
;         __builtin_amdgcn_global_load_lds((const unsigned*)((const char*)(gbase) + (voff)[_i]), (PG8_LAS unsigned*)(lds + (bufoff) + ldsw + _i * 8192), 16, 0, 0); } while (0)
; #define PG8_LDA(dst, b, h) do { _Pragma("unroll") for (int m = 0; m < 4; ++m) _Pragma("unroll") for (int k = 0; k < 2; ++k) dst[m][k] = *(const PG8_LAS bf16x8*)(lds + PG8_SA(b, h) + aoff + m * 2048 + k * 1024); } while (0)
; #define PG8_MMA(ai, bj, At, Bt) do { __builtin_amdgcn_s_setprio(1); _Pragma("unroll") for (int m = 0; m < 4; ++m) _Pragma("unroll") for (int n = 0; n < 2; ++n) _Pragma("unroll") for (int k = 0; k < 2; ++k) \
;         acc[ai][bj][m][n] = __builtin_amdgcn_mfma_f32_16x16x32_bf16(Bt[n][k], At[m][k], acc[ai][bj][m][n], 0, 0, 0); __builtin_amdgcn_s_setprio(0); } while (0)
; #define PG8_WAIT_V(n) asm volatile("s_waitcnt vmcnt(" #n ")" ::: "memory")
; #define PG8_WAIT_L(n) asm volatile("s_waitcnt lgkmcnt(" #n ")" ::: "memory")
; #define PG8_BAR __builtin_amdgcn_s_barrier()
; #define PG8_SCHED __builtin_amdgcn_sched_barrier(0)
; template <class Epi, class Sched, bool ALIGN_EPI = false, bool SP2 = false>
; __device__ __forceinline__ void gemm_phase(PG8_LAS unsigned char* lds, const Gemm g, const Sched S, const Epi E) {
;     ...
;         for (int t = 0; t < nt; t += 2) {
;             if constexpr (Epi::MIDT >= 0) { if (t == Epi::MIDT) E.mid(acc, cur, wr, fr); }
;             const bool last = (t == nt - 2);
;             const char* a1 = cA + (size_t)(t + 1) * kstep;
;             const char* a2 = last ? nA : cA + (size_t)(t + 2) * kstep; const char* b2 = last ? nB : cB + (size_t)(t + 2) * kstep;
;     ...
;             PG8_LDA(At, 1, 1); PG8_STAGE(PG8_SB(1, 0), b3, voffB); PG8_STAGE(PG8_SB(1, 1), b3 + hstep, voffB); PG8_STAGE(PG8_SA(1, 0), a3, voffA);
;             PG8_WAIT_V(8); PG8_WAIT_L(0); PG8_BAR; PG8_MMA(1, 0, At, B0); PG8_MMA(1, 1, At, B1); PG8_BAR; PG8_SCHED;
	s_add_i32 s46, s72, s8
	v_lshl_add_u64 v[210:211], v[210:211], 0, s[10:11]
	s_mov_b32 m0, s46
	ds_read_b128 v[160:163], v243 offset:49152
	ds_read_b128 v[164:167], v243 offset:50176
	ds_read_b128 v[168:171], v243 offset:51200
	ds_read_b128 v[172:175], v243 offset:52224
	ds_read_b128 v[176:179], v243 offset:53248
	ds_read_b128 v[180:183], v243 offset:54272
	ds_read_b128 v[184:187], v243 offset:55296
	ds_read_b128 v[206:209], v243 offset:56320
	global_load_lds_dwordx4 v[210:211], off
	s_add_i32 m0, s46, 0x2000
	s_add_u32 s46, s50, 0xb0080
	v_lshl_add_u64 v[210:211], v[212:213], 0, s[10:11]
	s_addc_u32 s47, s51, 0
	s_add_i32 s50, s73, s8
	global_load_lds_dwordx4 v[210:211], off
	v_lshl_add_u64 v[210:211], s[46:47], 0, v[192:193]
	s_mov_b32 m0, s50
	s_nop 0
	global_load_lds_dwordx4 v[210:211], off
	v_lshl_add_u64 v[210:211], s[46:47], 0, v[196:197]
	s_add_i32 m0, s50, 0x2000
	s_nop 0
	global_load_lds_dwordx4 v[210:211], off
	v_lshl_add_u64 v[210:211], v[214:215], 0, s[10:11]
	s_mov_b32 m0, s59
	s_nop 0
	global_load_lds_dwordx4 v[210:211], off
	v_lshl_add_u64 v[210:211], v[216:217], 0, s[10:11]
	s_mov_b32 m0, s60
	s_nop 0
	global_load_lds_dwordx4 v[210:211], off
	s_waitcnt vmcnt(8)
	s_waitcnt lgkmcnt(0)
	s_barrier
	s_setprio 1
	s_waitcnt lgkmcnt(0)
	v_mfma_f32_16x16x32_bf16 v[60:63], v[128:131], v[160:163], v[60:63]
	v_mfma_f32_16x16x32_bf16 v[56:59], v[136:139], v[160:163], v[56:59]
	v_mfma_f32_16x16x32_bf16 v[48:51], v[128:131], v[168:171], v[48:51]
	v_mfma_f32_16x16x32_bf16 v[40:43], v[136:139], v[168:171], v[40:43]
	v_mfma_f32_16x16x32_bf16 v[32:35], v[128:131], v[176:179], v[32:35]
	v_mfma_f32_16x16x32_bf16 v[24:27], v[136:139], v[176:179], v[24:27]
	v_mfma_f32_16x16x32_bf16 v[16:19], v[128:131], v[184:187], v[16:19]
	v_mfma_f32_16x16x32_bf16 v[8:11], v[136:139], v[184:187], v[8:11]
	v_mfma_f32_16x16x32_bf16 v[60:63], v[132:135], v[164:167], v[60:63]
	v_mfma_f32_16x16x32_bf16 v[56:59], v[140:143], v[164:167], v[56:59]
	v_mfma_f32_16x16x32_bf16 v[48:51], v[132:135], v[172:175], v[48:51]
	v_mfma_f32_16x16x32_bf16 v[40:43], v[140:143], v[172:175], v[40:43]
	v_mfma_f32_16x16x32_bf16 v[32:35], v[132:135], v[180:183], v[32:35]
	v_mfma_f32_16x16x32_bf16 v[24:27], v[140:143], v[180:183], v[24:27]
	v_mfma_f32_16x16x32_bf16 v[16:19], v[132:135], v[206:209], v[16:19]
	v_mfma_f32_16x16x32_bf16 v[8:11], v[140:143], v[206:209], v[8:11]
	s_setprio 0
	s_setprio 1
	v_mfma_f32_16x16x32_bf16 v[52:55], v[144:147], v[160:163], v[52:55]
	v_mfma_f32_16x16x32_bf16 v[44:47], v[152:155], v[160:163], v[44:47]
	v_mfma_f32_16x16x32_bf16 v[36:39], v[144:147], v[168:171], v[36:39]
	v_mfma_f32_16x16x32_bf16 v[28:31], v[152:155], v[168:171], v[28:31]
	v_mfma_f32_16x16x32_bf16 v[20:23], v[144:147], v[176:179], v[20:23]
	v_mfma_f32_16x16x32_bf16 v[12:15], v[152:155], v[176:179], v[12:15]
	v_mfma_f32_16x16x32_bf16 v[4:7], v[144:147], v[184:187], v[4:7]
	v_mfma_f32_16x16x32_bf16 v[0:3], v[152:155], v[184:187], v[0:3]
	s_add_i32 s71, s71, 2
	s_add_u32 s69, s69, 0x100
	s_addc_u32 s70, s70, 0
	s_cmp_gt_u32 s71, 41
	s_mov_b64 s[46:47], s[48:49]
	v_mfma_f32_16x16x32_bf16 v[52:55], v[148:151], v[164:167], v[52:55]
	v_mfma_f32_16x16x32_bf16 v[44:47], v[156:159], v[164:167], v[44:47]
	v_mfma_f32_16x16x32_bf16 v[36:39], v[148:151], v[172:175], v[36:39]
	v_mfma_f32_16x16x32_bf16 v[28:31], v[156:159], v[172:175], v[28:31]
	v_mfma_f32_16x16x32_bf16 v[20:23], v[148:151], v[180:183], v[20:23]
	v_mfma_f32_16x16x32_bf16 v[12:15], v[156:159], v[180:183], v[12:15]
	v_mfma_f32_16x16x32_bf16 v[4:7], v[148:151], v[206:209], v[4:7]
	v_mfma_f32_16x16x32_bf16 v[0:3], v[156:159], v[206:209], v[0:3]
	s_setprio 0
	s_barrier
	s_cbranch_scc0 .LBB0_1105
	s_and_b64 vcc, exec, s[16:17]
	s_cbranch_vccz .LBB0_1108
	s_barrier
